# noprio + 15 stage loads in saddr form (v_lshl_add_u64 removed) + 50 m0 s_nop removed: fewer loader issue slots in GEMM K-loops
# baseline (speedup 1.0000x reference)
; #define PG8_STAGE(bufoff, gbase, voff) do { _Pragma("unroll") for (int _i = 0; _i < 2; ++_i) \
;         __builtin_amdgcn_global_load_lds((const unsigned*)((const char*)(gbase) + (voff)[_i]), (LAS unsigned*)(lds + (bufoff) + ldsw + _i * 8192), 16, 0, 0); } while (0)
; #define PG8_WAIT_V(n) asm volatile("s_waitcnt vmcnt(" #n ")" ::: "memory")
; #define PG8_BAR __builtin_amdgcn_s_barrier()
; __device__ __forceinline__ int fresh_tid() { int t = threadIdx.x; asm volatile("" : "+v"(t)); return t; }
; template <class Epi, class Sched, bool ALIGN_EPI = true>
; __device__ __forceinline__ void gemm_phase(LAS unsigned char* lds, const Gemm g, const Sched& S, const Epi& E) {
;     const int tid = fresh_tid(), wid = __builtin_amdgcn_readfirstlane(tid >> 6), lane = tid & 63, wr = wid >> 2, wc = wid & 3, fr = lane & 15, fq = lane >> 4;
;     const int K = g.K, nt = K / BK;
;     unsigned voffA[2], voffB[2];
; #pragma unroll
;     for (int i = 0; i < 2; ++i) { int R, C; stage_rc(tid * 16 + i * 8192, R, C); const int Rb = Epi::PERM ? ((R & ~31) + perm32(R & 31)) : R;
;         voffA[i] = (unsigned)(R * K + C) * 2u; voffB[i] = (unsigned)(Rb * K + C) * 2u; }
;     const size_t kstep = (size_t)(BK * 2);
;     const size_t hstep = (size_t)HALF * K * 2;
;     const size_t tstep = 2 * hstep;
;     const unsigned ldsw = (unsigned)wid * 1024u;
;     const int aoff = lds_byte(wr * 64 + fr, fq * 8), boff = lds_byte(wc * 32 + fr, fq * 8);
;     ...
;     PG8_WAIT_V(2); PG8_BAR;
;     PG8_STAGE(PG8_SB(1, 0), cB + kstep, voffB); PG8_STAGE(PG8_SA(1, 0), cA + kstep, voffA); PG8_STAGE(PG8_SB(1, 1), cB + hstep + kstep, voffB);
;     PG8_WAIT_V(6); PG8_BAR;
.LBB0_192:
	s_mov_b64 s[22:23], 0x80
	s_and_b32 s5, s27, 3
	s_add_i32 m0, s44, 0x18000
	v_lshl_add_u64 v[6:7], v[6:7], 0, s[22:23]
	s_lshl_b32 s26, s28, 6
	s_lshl_b32 s9, s28, 13
	s_lshl_b32 s34, s27, 5
	s_lshl_b32 s5, s5, 12
	s_waitcnt vmcnt(2)
	s_barrier
	global_load_lds_dwordx4 v[6:7], off
	v_lshl_add_u64 v[4:5], v[4:5], 0, s[22:23]
	s_add_i32 m0, s44, 0x1a000
	s_add_i32 s54, s44, 0x8000
	s_add_i32 s55, s44, 0xa000
	global_load_lds_dwordx4 v[4:5], off
	v_lshl_add_u64 v[0:1], v[0:1], 0, s[22:23]
	s_mov_b32 m0, s54
	s_add_u32 s30, s10, 0x80080
	global_load_lds_dwordx4 v[0:1], off
	v_lshl_add_u64 v[0:1], v[2:3], 0, s[22:23]
	s_mov_b32 m0, s55
	s_addc_u32 s31, s11, 0
	global_load_lds_dwordx4 v[0:1], off
	s_add_i32 m0, s44, 0x1c000
	s_nop 0
	global_load_lds_dwordx4 v130, s[30:31]
	v_lshl_add_u64 v[0:1], s[30:31], 0, v[134:135]
	s_add_i32 m0, s44, 0x1e000
	v_lshrrev_b32_e32 v2, 1, v8
	global_load_lds_dwordx4 v[0:1], off
	v_and_b32_e32 v0, 15, v8
	v_or_b32_e32 v1, s26, v0
	v_and_b32_e32 v2, 24, v2
	v_lshlrev_b32_e32 v138, 6, v1
	v_lshlrev_b32_e32 v1, 1, v2
	s_movk_i32 s25, 0x3c0
	s_cmpk_lt_u32 s24, 0x100
	v_and_or_b32 v3, v138, s25, v1
	s_cselect_b64 s[24:25], -1, 0
	s_bfe_u32 s56, s27, 0x10001
	s_ashr_i32 s27, s26, 31
	s_lshl_b64 s[26:27], s[26:27], 2
	v_lshlrev_b32_e32 v136, 2, v0
	v_lshlrev_b32_e32 v0, 6, v0
	s_add_u32 s30, s6, s26
	v_or_b32_e32 v1, v1, v0
	v_lshl_or_b32 v148, s28, 12, v0
	s_addc_u32 s31, s7, s27
	v_lshlrev_b32_e32 v0, 15, v9
	v_and_b32_e32 v4, 32, v136
	s_add_u32 s26, s68, s26
	v_and_b32_e32 v0, 0xffff0000, v0
	v_bitop3_b32 v169, v1, s5, v4 bitop3:0xde
	s_addc_u32 s27, s69, s27
	v_lshl_add_u32 v0, v10, 12, v0
	v_and_b32_e32 v1, 1, v9
	v_lshl_add_u64 v[158:159], s[26:27], 0, v[136:137]
	s_add_u32 s27, s68, 0x8540000
	v_lshl_or_b32 v0, v1, 6, v0
	s_addc_u32 s57, s69, 0
	v_lshl_add_u32 v160, v11, 1, v0
	v_lshlrev_b32_e32 v0, 15, v12
	s_add_u32 s58, s68, 0x8520000
	v_and_b32_e32 v0, 0xffff0000, v0
	s_waitcnt vmcnt(6)
	s_addc_u32 s59, s69, 0
	v_lshl_add_u32 v0, v13, 12, v0
	v_and_b32_e32 v1, 1, v12
	v_bitop3_b32 v3, v3, s9, v4 bitop3:0xde
	s_mov_b32 s5, 0
	v_or_b32_e32 v142, 0x400, v138
	v_or_b32_e32 v144, 0x800, v138
	v_or_b32_e32 v146, 0xc00, v138
	v_or_b32_e32 v150, 0x400, v148
	v_or_b32_e32 v152, 0x800, v148
	v_or_b32_e32 v154, 0xc00, v148
	s_add_u32 s76, s68, 0x8560000
	v_lshl_or_b32 v0, v1, 6, v0
	v_and_or_b32 v140, s34, 32, v2
	v_ashrrev_i32_e32 v139, 31, v138
	v_ashrrev_i32_e32 v143, 31, v142
	v_ashrrev_i32_e32 v145, 31, v144
	v_ashrrev_i32_e32 v147, 31, v146
	v_ashrrev_i32_e32 v149, 31, v148
	v_ashrrev_i32_e32 v151, 31, v150
	v_ashrrev_i32_e32 v153, 31, v152
	v_ashrrev_i32_e32 v155, 31, v154
	v_lshl_add_u64 v[156:157], s[30:31], 0, v[136:137]
	s_addc_u32 s77, s69, 0
	v_mov_b32_e32 v161, v137
	v_lshl_add_u32 v162, v14, 1, v0
	v_mov_b32_e32 v163, v137
	s_add_i32 s78, 0, 0x10000
	s_add_i32 s79, 0, 0x14000
	v_add_u32_e32 v171, 0, v3
	s_mov_b32 s26, 0xbfb8aa3b
	s_mov_b32 s28, 0x3f317218
	v_mov_b32_e32 v179, 0xe0000
	s_mov_b32 s80, s5
	s_barrier
	s_branch .LBB0_194

; #define PG8_STAGE(bufoff, gbase, voff) do { _Pragma("unroll") for (int _i = 0; _i < 2; ++_i) \
;         __builtin_amdgcn_global_load_lds((const unsigned*)((const char*)(gbase) + (voff)[_i]), (LAS unsigned*)(lds + (bufoff) + ldsw + _i * 8192), 16, 0, 0); } while (0)
; #define PG8_LDA(dst, b, h) do { _Pragma("unroll") for (int m = 0; m < 4; ++m) _Pragma("unroll") for (int k = 0; k < 2; ++k) dst[m][k] = *(const LAS bf16x8*)(lds + PG8_SA(b, h) + aoff + m * 2048 + k * 1024); } while (0)
; #define PG8_LDB(dst, b, h) do { _Pragma("unroll") for (int n = 0; n < 2; ++n) _Pragma("unroll") for (int k = 0; k < 2; ++k) dst[n][k] = *(const LAS bf16x8*)(lds + PG8_SB(b, h) + boff + n * 2048 + k * 1024); } while (0)
; #define PG8_MMA(ai, bj, At, Bt) do { __builtin_amdgcn_s_setprio(1); _Pragma("unroll") for (int m = 0; m < 4; ++m) _Pragma("unroll") for (int n = 0; n < 2; ++n) _Pragma("unroll") for (int k = 0; k < 2; ++k) \
;         acc[ai][bj][m][n] = __builtin_amdgcn_mfma_f32_16x16x32_bf16(Bt[n][k], At[m][k], acc[ai][bj][m][n], 0, 0, 0); __builtin_amdgcn_s_setprio(0); } while (0)
; #define PG8_WAIT_V(n) asm volatile("s_waitcnt vmcnt(" #n ")" ::: "memory")
; #define PG8_WAIT_L(n) asm volatile("s_waitcnt lgkmcnt(" #n ")" ::: "memory")
; #define PG8_BAR __builtin_amdgcn_s_barrier()
; #define PG8_SCHED __builtin_amdgcn_sched_barrier(0)
; template <class Epi, class Sched, bool ALIGN_EPI = true>
; __device__ __forceinline__ void gemm_phase(LAS unsigned char* lds, const Gemm g, const Sched& S, const Epi& E) {
;     ...
;             PG8_LDB(B0, 0, 0); PG8_LDB(B1, 0, 1); PG8_SCHED; PG8_LDA(At, 0, 0); PG8_STAGE(PG8_SA(1, 1), a1 + hstep, voffA);
;             PG8_WAIT_V(8); PG8_WAIT_L(0); PG8_BAR; PG8_MMA(0, 0, At, B0); PG8_MMA(0, 1, At, B1); PG8_BAR; PG8_SCHED;
;             PG8_LDA(At, 0, 1); PG8_STAGE(PG8_SB(0, 0), b2, voffB); PG8_STAGE(PG8_SB(0, 1), b2 + hstep, voffB); PG8_STAGE(PG8_SA(0, 0), a2, voffA);
;             PG8_WAIT_V(8); PG8_WAIT_L(0); PG8_BAR; PG8_MMA(1, 0, At, B0); PG8_MMA(1, 1, At, B1); PG8_BAR; PG8_SCHED;
.LBB0_195:
	v_add_u32_e32 v136, s78, v169
	ds_read_b128 v[172:175], v136
	ds_read_b128 v[180:183], v136 offset:1024
	ds_read_b128 v[184:187], v136 offset:2048
	ds_read_b128 v[188:191], v136 offset:3072
	v_add_u32_e32 v136, s79, v169
	ds_read_b128 v[192:195], v136
	ds_read_b128 v[196:199], v136 offset:1024
	ds_read_b128 v[204:207], v136 offset:2048
	ds_read_b128 v[208:211], v136 offset:3072
	s_add_u32 s36, s34, 0xfff80080
	s_addc_u32 s37, s35, -1
	s_cmp_eq_u32 s89, 28
	s_cselect_b32 s39, s84, s37
	s_cselect_b32 s38, s85, s36
	s_cselect_b32 s37, s9, s88
	s_cselect_b32 s36, s86, s87
	v_lshl_add_u64 v[164:165], s[34:35], 0, v[160:161]
	s_add_i32 m0, s44, 0xc000
	ds_read_b128 v[212:215], v171
	ds_read_b128 v[216:219], v171 offset:1024
	ds_read_b128 v[220:223], v171 offset:2048
	ds_read_b128 v[224:227], v171 offset:3072
	ds_read_b128 v[228:231], v171 offset:4096
	ds_read_b128 v[232:235], v171 offset:5120
	ds_read_b128 v[236:239], v171 offset:6144
	ds_read_b128 v[240:243], v171 offset:7168
	global_load_lds_dwordx4 v[164:165], off
	s_add_i32 m0, s44, 0xe000
	v_lshl_add_u64 v[164:165], s[34:35], 0, v[162:163]
	global_load_lds_dwordx4 v[164:165], off
	s_waitcnt vmcnt(8)
	s_waitcnt lgkmcnt(0)
	s_barrier
	s_waitcnt lgkmcnt(0)
	v_mfma_f32_16x16x32_bf16 v[124:127], v[172:175], v[212:215], v[124:127]
	v_mfma_f32_16x16x32_bf16 v[120:123], v[184:187], v[212:215], v[120:123]
	v_mfma_f32_16x16x32_bf16 v[108:111], v[172:175], v[220:223], v[108:111]
	v_mfma_f32_16x16x32_bf16 v[104:107], v[184:187], v[220:223], v[104:107]
	v_mfma_f32_16x16x32_bf16 v[92:95], v[172:175], v[228:231], v[92:95]
	v_mfma_f32_16x16x32_bf16 v[88:91], v[184:187], v[228:231], v[88:91]
	v_mfma_f32_16x16x32_bf16 v[76:79], v[172:175], v[236:239], v[76:79]
	v_mfma_f32_16x16x32_bf16 v[72:75], v[184:187], v[236:239], v[72:75]
	v_mfma_f32_16x16x32_bf16 v[124:127], v[180:183], v[216:219], v[124:127]
	v_mfma_f32_16x16x32_bf16 v[120:123], v[188:191], v[216:219], v[120:123]
	v_mfma_f32_16x16x32_bf16 v[108:111], v[180:183], v[224:227], v[108:111]
	v_mfma_f32_16x16x32_bf16 v[104:107], v[188:191], v[224:227], v[104:107]
	v_mfma_f32_16x16x32_bf16 v[92:95], v[180:183], v[232:235], v[92:95]
	v_mfma_f32_16x16x32_bf16 v[88:91], v[188:191], v[232:235], v[88:91]
	v_mfma_f32_16x16x32_bf16 v[76:79], v[180:183], v[240:243], v[76:79]
	v_mfma_f32_16x16x32_bf16 v[72:75], v[188:191], v[240:243], v[72:75]
	v_mfma_f32_16x16x32_bf16 v[116:119], v[192:195], v[212:215], v[116:119]
	v_mfma_f32_16x16x32_bf16 v[112:115], v[204:207], v[212:215], v[112:115]
	v_mfma_f32_16x16x32_bf16 v[100:103], v[192:195], v[220:223], v[100:103]
	v_mfma_f32_16x16x32_bf16 v[96:99], v[204:207], v[220:223], v[96:99]
	v_mfma_f32_16x16x32_bf16 v[84:87], v[192:195], v[228:231], v[84:87]
	v_mfma_f32_16x16x32_bf16 v[80:83], v[204:207], v[228:231], v[80:83]
	v_mfma_f32_16x16x32_bf16 v[68:71], v[192:195], v[236:239], v[68:71]
	v_mfma_f32_16x16x32_bf16 v[64:67], v[204:207], v[236:239], v[64:67]
	v_mfma_f32_16x16x32_bf16 v[116:119], v[196:199], v[216:219], v[116:119]
	v_mfma_f32_16x16x32_bf16 v[112:115], v[208:211], v[216:219], v[112:115]
	v_mfma_f32_16x16x32_bf16 v[100:103], v[196:199], v[224:227], v[100:103]
	v_mfma_f32_16x16x32_bf16 v[96:99], v[208:211], v[224:227], v[96:99]
	v_mfma_f32_16x16x32_bf16 v[84:87], v[196:199], v[232:235], v[84:87]
	v_mfma_f32_16x16x32_bf16 v[80:83], v[208:211], v[232:235], v[80:83]
	v_mfma_f32_16x16x32_bf16 v[68:71], v[196:199], v[240:243], v[68:71]
	v_mfma_f32_16x16x32_bf16 v[64:67], v[208:211], v[240:243], v[64:67]
	s_barrier
	s_add_i32 s46, s78, s42
	v_lshl_add_u64 v[164:165], s[36:37], 0, v[130:131]
	s_mov_b32 m0, s46
	ds_read_b128 v[212:215], v171 offset:16384
	ds_read_b128 v[216:219], v171 offset:17408
	ds_read_b128 v[220:223], v171 offset:18432
	ds_read_b128 v[224:227], v171 offset:19456
	ds_read_b128 v[228:231], v171 offset:20480
	ds_read_b128 v[232:235], v171 offset:21504
	ds_read_b128 v[236:239], v171 offset:22528
	ds_read_b128 v[240:243], v171 offset:23552
	global_load_lds_dwordx4 v[164:165], off
	s_add_i32 m0, s46, 0x2000
	s_add_u32 s90, s36, 0x80000
	v_lshl_add_u64 v[176:177], s[36:37], 0, v[134:135]
	s_addc_u32 s91, s37, 0
	s_add_i32 s46, s79, s42
	global_load_lds_dwordx4 v[176:177], off
	v_lshl_add_u64 v[200:201], s[90:91], 0, v[130:131]
	s_mov_b32 m0, s46
	v_lshl_add_u64 v[244:245], s[38:39], 0, v[132:133]
	global_load_lds_dwordx4 v[200:201], off
	s_add_i32 m0, s46, 0x2000
	s_nop 0
	global_load_lds_dwordx4 v134, s[90:91]
	s_mov_b32 m0, s44
	v_lshl_add_u64 v[200:201], s[38:39], 0, v[128:129]
	global_load_lds_dwordx4 v[200:201], off
	s_mov_b32 m0, s50
	s_nop 0
	global_load_lds_dwordx4 v[244:245], off
	s_waitcnt vmcnt(8)
	s_waitcnt lgkmcnt(0)
	s_barrier
; #define PG8_STAGE(bufoff, gbase, voff) do { _Pragma("unroll") for (int _i = 0; _i < 2; ++_i) \
;         __builtin_amdgcn_global_load_lds((const unsigned*)((const char*)(gbase) + (voff)[_i]), (LAS unsigned*)(lds + (bufoff) + ldsw + _i * 8192), 16, 0, 0); } while (0)
; #define PG8_LDA(dst, b, h) do { _Pragma("unroll") for (int m = 0; m < 4; ++m) _Pragma("unroll") for (int k = 0; k < 2; ++k) dst[m][k] = *(const LAS bf16x8*)(lds + PG8_SA(b, h) + aoff + m * 2048 + k * 1024); } while (0)
; #define PG8_LDB(dst, b, h) do { _Pragma("unroll") for (int n = 0; n < 2; ++n) _Pragma("unroll") for (int k = 0; k < 2; ++k) dst[n][k] = *(const LAS bf16x8*)(lds + PG8_SB(b, h) + boff + n * 2048 + k * 1024); } while (0)
; #define PG8_MMA(ai, bj, At, Bt) do { __builtin_amdgcn_s_setprio(1); _Pragma("unroll") for (int m = 0; m < 4; ++m) _Pragma("unroll") for (int n = 0; n < 2; ++n) _Pragma("unroll") for (int k = 0; k < 2; ++k) \
;         acc[ai][bj][m][n] = __builtin_amdgcn_mfma_f32_16x16x32_bf16(Bt[n][k], At[m][k], acc[ai][bj][m][n], 0, 0, 0); __builtin_amdgcn_s_setprio(0); } while (0)
; #define PG8_WAIT_V(n) asm volatile("s_waitcnt vmcnt(" #n ")" ::: "memory")
; #define PG8_WAIT_L(n) asm volatile("s_waitcnt lgkmcnt(" #n ")" ::: "memory")
; #define PG8_BAR __builtin_amdgcn_s_barrier()
; #define PG8_SCHED __builtin_amdgcn_sched_barrier(0)
; template <class Epi, class Sched, bool ALIGN_EPI = true>
; __device__ __forceinline__ void gemm_phase(LAS unsigned char* lds, const Gemm g, const Sched& S, const Epi& E) {
;     ...
;             PG8_WAIT_V(8); PG8_WAIT_L(0); PG8_BAR; PG8_MMA(1, 0, At, B0); PG8_MMA(1, 1, At, B1); PG8_BAR; PG8_SCHED;
;             PG8_LDB(B0, 1, 0); PG8_LDB(B1, 1, 1); PG8_SCHED; PG8_LDA(At, 1, 0); PG8_STAGE(PG8_SA(0, 1), a2 + hstep, voffA);
;             PG8_WAIT_V(8); PG8_WAIT_L(0); PG8_BAR; PG8_MMA(0, 0, At, B0); PG8_MMA(0, 1, At, B1); PG8_BAR; PG8_SCHED;
	s_waitcnt lgkmcnt(0)
	v_mfma_f32_16x16x32_bf16 v[60:63], v[172:175], v[212:215], v[60:63]
	v_mfma_f32_16x16x32_bf16 v[56:59], v[184:187], v[212:215], v[56:59]
	v_mfma_f32_16x16x32_bf16 v[44:47], v[172:175], v[220:223], v[44:47]
	v_mfma_f32_16x16x32_bf16 v[40:43], v[184:187], v[220:223], v[40:43]
	v_mfma_f32_16x16x32_bf16 v[28:31], v[172:175], v[228:231], v[28:31]
	v_mfma_f32_16x16x32_bf16 v[24:27], v[184:187], v[228:231], v[24:27]
	v_mfma_f32_16x16x32_bf16 v[12:15], v[172:175], v[236:239], v[12:15]
	v_mfma_f32_16x16x32_bf16 v[8:11], v[184:187], v[236:239], v[8:11]
	v_mfma_f32_16x16x32_bf16 v[60:63], v[180:183], v[216:219], v[60:63]
	v_mfma_f32_16x16x32_bf16 v[56:59], v[188:191], v[216:219], v[56:59]
	v_mfma_f32_16x16x32_bf16 v[44:47], v[180:183], v[224:227], v[44:47]
	v_mfma_f32_16x16x32_bf16 v[40:43], v[188:191], v[224:227], v[40:43]
	v_mfma_f32_16x16x32_bf16 v[28:31], v[180:183], v[232:235], v[28:31]
	v_mfma_f32_16x16x32_bf16 v[24:27], v[188:191], v[232:235], v[24:27]
	v_mfma_f32_16x16x32_bf16 v[12:15], v[180:183], v[240:243], v[12:15]
	v_mfma_f32_16x16x32_bf16 v[8:11], v[188:191], v[240:243], v[8:11]
	v_mfma_f32_16x16x32_bf16 v[52:55], v[192:195], v[212:215], v[52:55]
	v_mfma_f32_16x16x32_bf16 v[48:51], v[204:207], v[212:215], v[48:51]
	v_mfma_f32_16x16x32_bf16 v[36:39], v[192:195], v[220:223], v[36:39]
	v_mfma_f32_16x16x32_bf16 v[32:35], v[204:207], v[220:223], v[32:35]
	v_mfma_f32_16x16x32_bf16 v[20:23], v[192:195], v[228:231], v[20:23]
	v_mfma_f32_16x16x32_bf16 v[16:19], v[204:207], v[228:231], v[16:19]
	v_mfma_f32_16x16x32_bf16 v[4:7], v[192:195], v[236:239], v[4:7]
	v_mfma_f32_16x16x32_bf16 v[0:3], v[204:207], v[236:239], v[0:3]
	v_mfma_f32_16x16x32_bf16 v[52:55], v[196:199], v[216:219], v[52:55]
	v_mfma_f32_16x16x32_bf16 v[48:51], v[208:211], v[216:219], v[48:51]
	v_mfma_f32_16x16x32_bf16 v[36:39], v[196:199], v[224:227], v[36:39]
	v_mfma_f32_16x16x32_bf16 v[32:35], v[208:211], v[224:227], v[32:35]
	v_mfma_f32_16x16x32_bf16 v[20:23], v[196:199], v[232:235], v[20:23]
	v_mfma_f32_16x16x32_bf16 v[16:19], v[208:211], v[232:235], v[16:19]
	v_mfma_f32_16x16x32_bf16 v[4:7], v[196:199], v[240:243], v[4:7]
	v_mfma_f32_16x16x32_bf16 v[0:3], v[208:211], v[240:243], v[0:3]
	s_barrier
	s_add_i32 s46, 0, 0x18000
	v_add_u32_e32 v136, s46, v169
	s_add_i32 s47, 0, 0x1c000
	ds_read_b128 v[172:175], v136
	ds_read_b128 v[180:183], v136 offset:1024
	ds_read_b128 v[184:187], v136 offset:2048
	ds_read_b128 v[188:191], v136 offset:3072
	v_add_u32_e32 v136, s47, v169
	ds_read_b128 v[192:195], v136
	ds_read_b128 v[196:199], v136 offset:1024
	ds_read_b128 v[204:207], v136 offset:2048
	ds_read_b128 v[208:211], v136 offset:3072
	s_add_u32 s38, s38, 0x80000
	s_addc_u32 s39, s39, 0
	s_mov_b32 m0, s52
	v_lshl_add_u64 v[246:247], s[38:39], 0, v[128:129]
	ds_read_b128 v[212:215], v171 offset:32768
	ds_read_b128 v[216:219], v171 offset:33792
	ds_read_b128 v[220:223], v171 offset:34816
	ds_read_b128 v[224:227], v171 offset:35840
	ds_read_b128 v[228:231], v171 offset:36864
	ds_read_b128 v[232:235], v171 offset:37888
	ds_read_b128 v[236:239], v171 offset:38912
	ds_read_b128 v[240:243], v171 offset:39936
	global_load_lds_dwordx4 v[246:247], off
	s_mov_b32 m0, s53
	v_lshl_add_u64 v[246:247], s[38:39], 0, v[132:133]
	global_load_lds_dwordx4 v[246:247], off
	s_waitcnt vmcnt(8)
	s_waitcnt lgkmcnt(0)
	s_barrier
	s_waitcnt lgkmcnt(0)
	v_mfma_f32_16x16x32_bf16 v[124:127], v[172:175], v[212:215], v[124:127]
	v_mfma_f32_16x16x32_bf16 v[120:123], v[184:187], v[212:215], v[120:123]
	v_mfma_f32_16x16x32_bf16 v[108:111], v[172:175], v[220:223], v[108:111]
	v_mfma_f32_16x16x32_bf16 v[104:107], v[184:187], v[220:223], v[104:107]
	v_mfma_f32_16x16x32_bf16 v[92:95], v[172:175], v[228:231], v[92:95]
	v_mfma_f32_16x16x32_bf16 v[88:91], v[184:187], v[228:231], v[88:91]
	v_mfma_f32_16x16x32_bf16 v[76:79], v[172:175], v[236:239], v[76:79]
	v_mfma_f32_16x16x32_bf16 v[72:75], v[184:187], v[236:239], v[72:75]
	v_mfma_f32_16x16x32_bf16 v[124:127], v[180:183], v[216:219], v[124:127]
	v_mfma_f32_16x16x32_bf16 v[120:123], v[188:191], v[216:219], v[120:123]
	v_mfma_f32_16x16x32_bf16 v[108:111], v[180:183], v[224:227], v[108:111]
	v_mfma_f32_16x16x32_bf16 v[104:107], v[188:191], v[224:227], v[104:107]
	v_mfma_f32_16x16x32_bf16 v[92:95], v[180:183], v[232:235], v[92:95]
	v_mfma_f32_16x16x32_bf16 v[88:91], v[188:191], v[232:235], v[88:91]
	v_mfma_f32_16x16x32_bf16 v[76:79], v[180:183], v[240:243], v[76:79]
	v_mfma_f32_16x16x32_bf16 v[72:75], v[188:191], v[240:243], v[72:75]
	v_mfma_f32_16x16x32_bf16 v[116:119], v[192:195], v[212:215], v[116:119]
	v_mfma_f32_16x16x32_bf16 v[112:115], v[204:207], v[212:215], v[112:115]
	v_mfma_f32_16x16x32_bf16 v[100:103], v[192:195], v[220:223], v[100:103]
	v_mfma_f32_16x16x32_bf16 v[96:99], v[204:207], v[220:223], v[96:99]
	v_mfma_f32_16x16x32_bf16 v[84:87], v[192:195], v[228:231], v[84:87]
	v_mfma_f32_16x16x32_bf16 v[80:83], v[204:207], v[228:231], v[80:83]
	v_mfma_f32_16x16x32_bf16 v[68:71], v[192:195], v[236:239], v[68:71]
	v_mfma_f32_16x16x32_bf16 v[64:67], v[204:207], v[236:239], v[64:67]
	v_mfma_f32_16x16x32_bf16 v[116:119], v[196:199], v[216:219], v[116:119]
	v_mfma_f32_16x16x32_bf16 v[112:115], v[208:211], v[216:219], v[112:115]
	v_mfma_f32_16x16x32_bf16 v[100:103], v[196:199], v[224:227], v[100:103]
	v_mfma_f32_16x16x32_bf16 v[96:99], v[208:211], v[224:227], v[96:99]
	v_mfma_f32_16x16x32_bf16 v[84:87], v[196:199], v[232:235], v[84:87]
	v_mfma_f32_16x16x32_bf16 v[80:83], v[208:211], v[232:235], v[80:83]
	v_mfma_f32_16x16x32_bf16 v[68:71], v[196:199], v[240:243], v[68:71]
	v_mfma_f32_16x16x32_bf16 v[64:67], v[208:211], v[240:243], v[64:67]
	s_barrier
; #define PG8_STAGE(bufoff, gbase, voff) do { _Pragma("unroll") for (int _i = 0; _i < 2; ++_i) \
;         __builtin_amdgcn_global_load_lds((const unsigned*)((const char*)(gbase) + (voff)[_i]), (LAS unsigned*)(lds + (bufoff) + ldsw + _i * 8192), 16, 0, 0); } while (0)
; #define PG8_LDA(dst, b, h) do { _Pragma("unroll") for (int m = 0; m < 4; ++m) _Pragma("unroll") for (int k = 0; k < 2; ++k) dst[m][k] = *(const LAS bf16x8*)(lds + PG8_SA(b, h) + aoff + m * 2048 + k * 1024); } while (0)
; #define PG8_MMA(ai, bj, At, Bt) do { __builtin_amdgcn_s_setprio(1); _Pragma("unroll") for (int m = 0; m < 4; ++m) _Pragma("unroll") for (int n = 0; n < 2; ++n) _Pragma("unroll") for (int k = 0; k < 2; ++k) \
;         acc[ai][bj][m][n] = __builtin_amdgcn_mfma_f32_16x16x32_bf16(Bt[n][k], At[m][k], acc[ai][bj][m][n], 0, 0, 0); __builtin_amdgcn_s_setprio(0); } while (0)
; #define PG8_WAIT_V(n) asm volatile("s_waitcnt vmcnt(" #n ")" ::: "memory")
; #define PG8_WAIT_L(n) asm volatile("s_waitcnt lgkmcnt(" #n ")" ::: "memory")
; #define PG8_BAR __builtin_amdgcn_s_barrier()
; #define PG8_SCHED __builtin_amdgcn_sched_barrier(0)
; template <class Epi, class Sched, bool ALIGN_EPI = true>
; __device__ __forceinline__ void gemm_phase(LAS unsigned char* lds, const Gemm g, const Sched& S, const Epi& E) {
;     ...
;             PG8_LDA(At, 1, 1); PG8_STAGE(PG8_SB(1, 0), b3, voffB); PG8_STAGE(PG8_SB(1, 1), b3 + hstep, voffB); PG8_STAGE(PG8_SA(1, 0), a3, voffA);
;             PG8_WAIT_V(8); PG8_WAIT_L(0); PG8_BAR; PG8_MMA(1, 0, At, B0); PG8_MMA(1, 1, At, B1); PG8_BAR; PG8_SCHED;
;         }
;         if constexpr (ALIGN_EPI) { if (wr == 0) PG8_BAR; }
;         E(acc, cur, wr, wc, fr, fq);
;         if (!has_next) break;
	s_add_i32 s38, s46, s42
	v_lshl_add_u64 v[164:165], v[164:165], 0, s[22:23]
	s_mov_b32 m0, s38
	ds_read_b128 v[212:215], v171 offset:49152
	ds_read_b128 v[216:219], v171 offset:50176
	ds_read_b128 v[220:223], v171 offset:51200
	ds_read_b128 v[224:227], v171 offset:52224
	ds_read_b128 v[228:231], v171 offset:53248
	ds_read_b128 v[232:235], v171 offset:54272
	ds_read_b128 v[236:239], v171 offset:55296
	ds_read_b128 v[240:243], v171 offset:56320
	global_load_lds_dwordx4 v[164:165], off
	s_add_i32 m0, s38, 0x2000
	s_add_u32 s36, s36, 0x80080
	v_lshl_add_u64 v[164:165], v[176:177], 0, s[22:23]
	s_addc_u32 s37, s37, 0
	s_add_i32 s38, s47, s42
	global_load_lds_dwordx4 v[164:165], off
	s_mov_b32 m0, s38
	s_nop 0
	global_load_lds_dwordx4 v130, s[36:37]
	s_add_i32 m0, s38, 0x2000
	s_nop 0
	global_load_lds_dwordx4 v134, s[36:37]
	s_mov_b32 m0, s54
	v_lshl_add_u64 v[164:165], v[200:201], 0, s[22:23]
	global_load_lds_dwordx4 v[164:165], off
	s_mov_b32 m0, s55
	v_lshl_add_u64 v[164:165], v[244:245], 0, s[22:23]
	global_load_lds_dwordx4 v[164:165], off
	s_waitcnt vmcnt(8)
	s_waitcnt lgkmcnt(0)
	s_barrier
	s_waitcnt lgkmcnt(0)
	v_mfma_f32_16x16x32_bf16 v[60:63], v[172:175], v[212:215], v[60:63]
	v_mfma_f32_16x16x32_bf16 v[56:59], v[184:187], v[212:215], v[56:59]
	v_mfma_f32_16x16x32_bf16 v[44:47], v[172:175], v[220:223], v[44:47]
	v_mfma_f32_16x16x32_bf16 v[40:43], v[184:187], v[220:223], v[40:43]
	v_mfma_f32_16x16x32_bf16 v[28:31], v[172:175], v[228:231], v[28:31]
	v_mfma_f32_16x16x32_bf16 v[24:27], v[184:187], v[228:231], v[24:27]
	v_mfma_f32_16x16x32_bf16 v[12:15], v[172:175], v[236:239], v[12:15]
	v_mfma_f32_16x16x32_bf16 v[8:11], v[184:187], v[236:239], v[8:11]
	v_mfma_f32_16x16x32_bf16 v[60:63], v[180:183], v[216:219], v[60:63]
	v_mfma_f32_16x16x32_bf16 v[56:59], v[188:191], v[216:219], v[56:59]
	v_mfma_f32_16x16x32_bf16 v[44:47], v[180:183], v[224:227], v[44:47]
	v_mfma_f32_16x16x32_bf16 v[40:43], v[188:191], v[224:227], v[40:43]
	v_mfma_f32_16x16x32_bf16 v[28:31], v[180:183], v[232:235], v[28:31]
	v_mfma_f32_16x16x32_bf16 v[24:27], v[188:191], v[232:235], v[24:27]
	v_mfma_f32_16x16x32_bf16 v[12:15], v[180:183], v[240:243], v[12:15]
	v_mfma_f32_16x16x32_bf16 v[8:11], v[188:191], v[240:243], v[8:11]
	v_mfma_f32_16x16x32_bf16 v[52:55], v[192:195], v[212:215], v[52:55]
	v_mfma_f32_16x16x32_bf16 v[48:51], v[204:207], v[212:215], v[48:51]
	v_mfma_f32_16x16x32_bf16 v[36:39], v[192:195], v[220:223], v[36:39]
	v_mfma_f32_16x16x32_bf16 v[32:35], v[204:207], v[220:223], v[32:35]
	v_mfma_f32_16x16x32_bf16 v[20:23], v[192:195], v[228:231], v[20:23]
	v_mfma_f32_16x16x32_bf16 v[16:19], v[204:207], v[228:231], v[16:19]
	v_mfma_f32_16x16x32_bf16 v[4:7], v[192:195], v[236:239], v[4:7]
	v_mfma_f32_16x16x32_bf16 v[0:3], v[204:207], v[236:239], v[0:3]
	v_mfma_f32_16x16x32_bf16 v[52:55], v[196:199], v[216:219], v[52:55]
	v_mfma_f32_16x16x32_bf16 v[48:51], v[208:211], v[216:219], v[48:51]
	v_mfma_f32_16x16x32_bf16 v[36:39], v[196:199], v[224:227], v[36:39]
	v_mfma_f32_16x16x32_bf16 v[32:35], v[208:211], v[224:227], v[32:35]
	v_mfma_f32_16x16x32_bf16 v[20:23], v[196:199], v[232:235], v[20:23]
	v_mfma_f32_16x16x32_bf16 v[16:19], v[208:211], v[232:235], v[16:19]
	v_mfma_f32_16x16x32_bf16 v[4:7], v[196:199], v[240:243], v[4:7]
	v_mfma_f32_16x16x32_bf16 v[0:3], v[208:211], v[240:243], v[0:3]
	s_barrier
	s_add_i32 s89, s89, 2
	s_add_u32 s34, s34, 0x100
	s_addc_u32 s35, s35, 0
	s_add_u32 s87, s87, 0x100
	s_addc_u32 s88, s88, 0
	s_cmp_gt_u32 s89, 29
	s_cbranch_scc0 .LBB0_195
	s_and_b64 vcc, exec, s[24:25]
	s_cbranch_vccnz .LBB0_202
	s_lshr_b32 s9, s81, 2
	s_cmp_lt_i32 s9, 1
	s_mov_b64 s[34:35], -1
	s_cbranch_scc0 .LBB0_203

; #define PG8_STAGE(bufoff, gbase, voff) do { _Pragma("unroll") for (int _i = 0; _i < 2; ++_i) \
;         __builtin_amdgcn_global_load_lds((const unsigned*)((const char*)(gbase) + (voff)[_i]), (LAS unsigned*)(lds + (bufoff) + ldsw + _i * 8192), 16, 0, 0); } while (0)
; #define PG8_WAIT_V(n) asm volatile("s_waitcnt vmcnt(" #n ")" ::: "memory")
; #define PG8_BAR __builtin_amdgcn_s_barrier()
; template <class Epi, class Sched, bool ALIGN_EPI = true>
; __device__ __forceinline__ void gemm_phase(LAS unsigned char* lds, const Gemm g, const Sched& S, const Epi& E) {
;     ...
;     PG8_STAGE(PG8_SB(0, 0), cB, voffB); PG8_STAGE(PG8_SB(0, 1), cB + hstep, voffB); PG8_STAGE(PG8_SA(0, 0), cA, voffA); PG8_STAGE(PG8_SA(0, 1), cA + hstep, voffA);
;     if (wr == 1) PG8_BAR;
;     PG8_WAIT_V(2); PG8_BAR;
;     PG8_STAGE(PG8_SB(1, 0), cB + kstep, voffB); PG8_STAGE(PG8_SA(1, 0), cA + kstep, voffA); PG8_STAGE(PG8_SB(1, 1), cB + hstep + kstep, voffB);
;     PG8_WAIT_V(6); PG8_BAR;
.LBB0_644:
	s_add_u32 s14, s68, 0x8500000
	s_addc_u32 s15, s69, 0
	s_add_u32 s16, s68, 0x50000
	s_addc_u32 s17, s69, 0
	s_lshl_b32 s7, s18, 5
	s_mov_b64 s[18:19], 0x80
	s_and_b32 s7, s7, 0x60
	s_add_i32 m0, s37, 0x18000
	v_lshl_add_u64 v[6:7], v[6:7], 0, s[18:19]
	s_lshl_b32 s5, s21, 13
	s_lshl_b32 s24, s7, 7
	s_waitcnt vmcnt(2)
	s_barrier
	global_load_lds_dwordx4 v[6:7], off
	v_lshl_add_u64 v[4:5], v[4:5], 0, s[18:19]
	s_add_i32 m0, s37, 0x1a000
	s_add_i32 s41, s37, 0x8000
	s_add_i32 s42, s37, 0xa000
	global_load_lds_dwordx4 v[4:5], off
	v_lshl_add_u64 v[0:1], v[0:1], 0, s[18:19]
	s_mov_b32 m0, s41
	s_add_u32 s22, s8, 0x80080
	global_load_lds_dwordx4 v[0:1], off
	v_lshl_add_u64 v[0:1], v[2:3], 0, s[18:19]
	s_mov_b32 m0, s42
	s_addc_u32 s23, s9, 0
	global_load_lds_dwordx4 v[0:1], off
	s_add_i32 m0, s37, 0x1c000
	s_nop 0
	global_load_lds_dwordx4 v130, s[22:23]
	v_lshl_add_u64 v[0:1], s[22:23], 0, v[134:135]
	s_add_i32 m0, s37, 0x1e000
	s_cmpk_lt_u32 s20, 0x100
	global_load_lds_dwordx4 v[0:1], off
	v_lshrrev_b32_e32 v1, 1, v8
	v_and_b32_e32 v1, 24, v1
	v_and_b32_e32 v0, 15, v8
	v_lshlrev_b32_e32 v2, 1, v1
	v_lshl_or_b32 v144, s21, 6, v0
	v_lshl_or_b32 v0, v0, 6, v2
	v_lshlrev_b32_e32 v2, 2, v8
	v_and_b32_e32 v2, 32, v2
	v_bitop3_b32 v3, v0, s5, v2 bitop3:0xde
	v_bitop3_b32 v145, v0, s24, v2 bitop3:0xde
	v_lshlrev_b32_e32 v0, 15, v9
	v_and_b32_e32 v0, 0xffff0000, v0
	v_or_b32_e32 v146, s7, v1
	v_lshl_add_u32 v0, v10, 12, v0
	v_and_b32_e32 v1, 1, v9
	v_lshl_or_b32 v0, v1, 6, v0
	v_lshl_add_u32 v136, v11, 1, v0
	v_lshlrev_b32_e32 v0, 15, v12
	v_and_b32_e32 v0, 0xffff0000, v0
	s_waitcnt vmcnt(6)
	v_lshl_add_u32 v0, v13, 12, v0
	v_and_b32_e32 v1, 1, v12
	s_mov_b32 s5, 0
	s_cselect_b64 s[20:21], -1, 0
	v_lshl_or_b32 v0, v1, 6, v0
	s_add_i32 s43, 0, 0x10000
	s_add_i32 s44, 0, 0x14000
	v_mov_b32_e32 v137, v131
	v_lshl_add_u32 v138, v14, 1, v0
	v_mov_b32_e32 v139, v131
	v_add_u32_e32 v147, s43, v145
	v_add_u32_e32 v148, s44, v145
	v_add_u32_e32 v149, 0, v3
	v_mov_b32_e32 v150, 0x358637bd
	s_movk_i32 s45, 0x2c00
	s_mov_b32 s48, s5
	s_barrier
	s_branch .LBB0_646

; #define PG8_STAGE(bufoff, gbase, voff) do { _Pragma("unroll") for (int _i = 0; _i < 2; ++_i) \
;         __builtin_amdgcn_global_load_lds((const unsigned*)((const char*)(gbase) + (voff)[_i]), (LAS unsigned*)(lds + (bufoff) + ldsw + _i * 8192), 16, 0, 0); } while (0)
; #define PG8_LDA(dst, b, h) do { _Pragma("unroll") for (int m = 0; m < 4; ++m) _Pragma("unroll") for (int k = 0; k < 2; ++k) dst[m][k] = *(const LAS bf16x8*)(lds + PG8_SA(b, h) + aoff + m * 2048 + k * 1024); } while (0)
; #define PG8_LDB(dst, b, h) do { _Pragma("unroll") for (int n = 0; n < 2; ++n) _Pragma("unroll") for (int k = 0; k < 2; ++k) dst[n][k] = *(const LAS bf16x8*)(lds + PG8_SB(b, h) + boff + n * 2048 + k * 1024); } while (0)
; #define PG8_MMA(ai, bj, At, Bt) do { __builtin_amdgcn_s_setprio(1); _Pragma("unroll") for (int m = 0; m < 4; ++m) _Pragma("unroll") for (int n = 0; n < 2; ++n) _Pragma("unroll") for (int k = 0; k < 2; ++k) \
;         acc[ai][bj][m][n] = __builtin_amdgcn_mfma_f32_16x16x32_bf16(Bt[n][k], At[m][k], acc[ai][bj][m][n], 0, 0, 0); __builtin_amdgcn_s_setprio(0); } while (0)
; #define PG8_WAIT_V(n) asm volatile("s_waitcnt vmcnt(" #n ")" ::: "memory")
; #define PG8_WAIT_L(n) asm volatile("s_waitcnt lgkmcnt(" #n ")" ::: "memory")
; #define PG8_BAR __builtin_amdgcn_s_barrier()
; #define PG8_SCHED __builtin_amdgcn_sched_barrier(0)
; template <class Epi, class Sched, bool ALIGN_EPI = true>
; __device__ __forceinline__ void gemm_phase(LAS unsigned char* lds, const Gemm g, const Sched& S, const Epi& E) {
;     ...
;             PG8_LDB(B0, 0, 0); PG8_LDB(B1, 0, 1); PG8_SCHED; PG8_LDA(At, 0, 0); PG8_STAGE(PG8_SA(1, 1), a1 + hstep, voffA);
;             PG8_WAIT_V(8); PG8_WAIT_L(0); PG8_BAR; PG8_MMA(0, 0, At, B0); PG8_MMA(0, 1, At, B1); PG8_BAR; PG8_SCHED;
;             PG8_LDA(At, 0, 1); PG8_STAGE(PG8_SB(0, 0), b2, voffB); PG8_STAGE(PG8_SB(0, 1), b2 + hstep, voffB); PG8_STAGE(PG8_SA(0, 0), a2, voffA);
;             PG8_WAIT_V(8); PG8_WAIT_L(0); PG8_BAR; PG8_MMA(1, 0, At, B0); PG8_MMA(1, 1, At, B1); PG8_BAR; PG8_SCHED;
.LBB0_647:
	ds_read_b128 v[152:155], v147
	ds_read_b128 v[156:159], v147 offset:1024
	ds_read_b128 v[160:163], v147 offset:2048
	ds_read_b128 v[164:167], v147 offset:3072
	ds_read_b128 v[168:171], v148
	ds_read_b128 v[172:175], v148 offset:1024
	ds_read_b128 v[176:179], v148 offset:2048
	ds_read_b128 v[180:183], v148 offset:3072
	s_add_u32 s26, s24, 0xfff80080
	s_addc_u32 s27, s25, -1
	s_cmp_eq_u32 s56, 28
	s_cselect_b32 s29, s51, s27
	s_cselect_b32 s28, s52, s26
	s_cselect_b32 s27, s7, s55
	s_cselect_b32 s26, s53, s54
	v_lshl_add_u64 v[140:141], s[24:25], 0, v[136:137]
	s_add_i32 m0, s37, 0xc000
	ds_read_b128 v[184:187], v149
	ds_read_b128 v[188:191], v149 offset:1024
	ds_read_b128 v[192:195], v149 offset:2048
	ds_read_b128 v[196:199], v149 offset:3072
	ds_read_b128 v[204:207], v149 offset:4096
	ds_read_b128 v[208:211], v149 offset:5120
	ds_read_b128 v[212:215], v149 offset:6144
	ds_read_b128 v[216:219], v149 offset:7168
	global_load_lds_dwordx4 v[140:141], off
	s_add_i32 m0, s37, 0xe000
	s_nop 0
	global_load_lds_dwordx4 v138, s[24:25]
	s_waitcnt vmcnt(8)
	s_waitcnt lgkmcnt(0)
	s_barrier
	s_waitcnt lgkmcnt(0)
	v_mfma_f32_16x16x32_bf16 v[112:115], v[152:155], v[184:187], v[112:115]
	v_mfma_f32_16x16x32_bf16 v[108:111], v[160:163], v[184:187], v[108:111]
	v_mfma_f32_16x16x32_bf16 v[100:103], v[152:155], v[192:195], v[100:103]
	v_mfma_f32_16x16x32_bf16 v[96:99], v[160:163], v[192:195], v[96:99]
	v_mfma_f32_16x16x32_bf16 v[92:95], v[152:155], v[204:207], v[92:95]
	v_mfma_f32_16x16x32_bf16 v[84:87], v[160:163], v[204:207], v[84:87]
	v_mfma_f32_16x16x32_bf16 v[76:79], v[152:155], v[212:215], v[76:79]
	v_mfma_f32_16x16x32_bf16 v[68:71], v[160:163], v[212:215], v[68:71]
	v_mfma_f32_16x16x32_bf16 v[112:115], v[156:159], v[188:191], v[112:115]
	v_mfma_f32_16x16x32_bf16 v[108:111], v[164:167], v[188:191], v[108:111]
	v_mfma_f32_16x16x32_bf16 v[100:103], v[156:159], v[196:199], v[100:103]
	v_mfma_f32_16x16x32_bf16 v[96:99], v[164:167], v[196:199], v[96:99]
	v_mfma_f32_16x16x32_bf16 v[92:95], v[156:159], v[208:211], v[92:95]
	v_mfma_f32_16x16x32_bf16 v[84:87], v[164:167], v[208:211], v[84:87]
	v_mfma_f32_16x16x32_bf16 v[76:79], v[156:159], v[216:219], v[76:79]
	v_mfma_f32_16x16x32_bf16 v[68:71], v[164:167], v[216:219], v[68:71]
	v_mfma_f32_16x16x32_bf16 v[124:127], v[168:171], v[184:187], v[124:127]
	v_mfma_f32_16x16x32_bf16 v[120:123], v[176:179], v[184:187], v[120:123]
	v_mfma_f32_16x16x32_bf16 v[116:119], v[168:171], v[192:195], v[116:119]
	v_mfma_f32_16x16x32_bf16 v[104:107], v[176:179], v[192:195], v[104:107]
	v_mfma_f32_16x16x32_bf16 v[88:91], v[168:171], v[204:207], v[88:91]
	v_mfma_f32_16x16x32_bf16 v[80:83], v[176:179], v[204:207], v[80:83]
	v_mfma_f32_16x16x32_bf16 v[72:75], v[168:171], v[212:215], v[72:75]
	v_mfma_f32_16x16x32_bf16 v[64:67], v[176:179], v[212:215], v[64:67]
	v_mfma_f32_16x16x32_bf16 v[124:127], v[172:175], v[188:191], v[124:127]
	v_mfma_f32_16x16x32_bf16 v[120:123], v[180:183], v[188:191], v[120:123]
	v_mfma_f32_16x16x32_bf16 v[116:119], v[172:175], v[196:199], v[116:119]
	v_mfma_f32_16x16x32_bf16 v[104:107], v[180:183], v[196:199], v[104:107]
	v_mfma_f32_16x16x32_bf16 v[88:91], v[172:175], v[208:211], v[88:91]
	v_mfma_f32_16x16x32_bf16 v[80:83], v[180:183], v[208:211], v[80:83]
	v_mfma_f32_16x16x32_bf16 v[72:75], v[172:175], v[216:219], v[72:75]
	v_mfma_f32_16x16x32_bf16 v[64:67], v[180:183], v[216:219], v[64:67]
	s_barrier
	s_add_i32 s46, s43, s36
	v_lshl_add_u64 v[140:141], s[26:27], 0, v[130:131]
	s_mov_b32 m0, s46
	ds_read_b128 v[184:187], v149 offset:16384
	ds_read_b128 v[188:191], v149 offset:17408
	ds_read_b128 v[192:195], v149 offset:18432
	ds_read_b128 v[196:199], v149 offset:19456
	ds_read_b128 v[204:207], v149 offset:20480
	ds_read_b128 v[208:211], v149 offset:21504
	ds_read_b128 v[212:215], v149 offset:22528
	ds_read_b128 v[216:219], v149 offset:23552
	global_load_lds_dwordx4 v[140:141], off
	s_add_i32 m0, s46, 0x2000
	s_add_u32 s46, s26, 0x80000
	v_lshl_add_u64 v[200:201], s[26:27], 0, v[134:135]
	s_addc_u32 s47, s27, 0
	s_add_i32 s57, s44, s36
	global_load_lds_dwordx4 v[200:201], off
	v_lshl_add_u64 v[220:221], s[46:47], 0, v[130:131]
	s_mov_b32 m0, s57
	v_lshl_add_u64 v[222:223], s[28:29], 0, v[132:133]
	global_load_lds_dwordx4 v[220:221], off
	s_add_i32 m0, s57, 0x2000
	s_nop 0
	global_load_lds_dwordx4 v134, s[46:47]
	s_mov_b32 m0, s37
	v_lshl_add_u64 v[220:221], s[28:29], 0, v[128:129]
	global_load_lds_dwordx4 v[220:221], off
	s_mov_b32 m0, s38
	s_nop 0
	global_load_lds_dwordx4 v[222:223], off
	s_waitcnt vmcnt(8)
	s_waitcnt lgkmcnt(0)
	s_barrier
; #define PG8_STAGE(bufoff, gbase, voff) do { _Pragma("unroll") for (int _i = 0; _i < 2; ++_i) \
;         __builtin_amdgcn_global_load_lds((const unsigned*)((const char*)(gbase) + (voff)[_i]), (LAS unsigned*)(lds + (bufoff) + ldsw + _i * 8192), 16, 0, 0); } while (0)
; #define PG8_LDA(dst, b, h) do { _Pragma("unroll") for (int m = 0; m < 4; ++m) _Pragma("unroll") for (int k = 0; k < 2; ++k) dst[m][k] = *(const LAS bf16x8*)(lds + PG8_SA(b, h) + aoff + m * 2048 + k * 1024); } while (0)
; #define PG8_LDB(dst, b, h) do { _Pragma("unroll") for (int n = 0; n < 2; ++n) _Pragma("unroll") for (int k = 0; k < 2; ++k) dst[n][k] = *(const LAS bf16x8*)(lds + PG8_SB(b, h) + boff + n * 2048 + k * 1024); } while (0)
; #define PG8_MMA(ai, bj, At, Bt) do { __builtin_amdgcn_s_setprio(1); _Pragma("unroll") for (int m = 0; m < 4; ++m) _Pragma("unroll") for (int n = 0; n < 2; ++n) _Pragma("unroll") for (int k = 0; k < 2; ++k) \
;         acc[ai][bj][m][n] = __builtin_amdgcn_mfma_f32_16x16x32_bf16(Bt[n][k], At[m][k], acc[ai][bj][m][n], 0, 0, 0); __builtin_amdgcn_s_setprio(0); } while (0)
; #define PG8_WAIT_V(n) asm volatile("s_waitcnt vmcnt(" #n ")" ::: "memory")
; #define PG8_WAIT_L(n) asm volatile("s_waitcnt lgkmcnt(" #n ")" ::: "memory")
; #define PG8_BAR __builtin_amdgcn_s_barrier()
; #define PG8_SCHED __builtin_amdgcn_sched_barrier(0)
; template <class Epi, class Sched, bool ALIGN_EPI = true>
; __device__ __forceinline__ void gemm_phase(LAS unsigned char* lds, const Gemm g, const Sched& S, const Epi& E) {
;     ...
;             PG8_WAIT_V(8); PG8_WAIT_L(0); PG8_BAR; PG8_MMA(1, 0, At, B0); PG8_MMA(1, 1, At, B1); PG8_BAR; PG8_SCHED;
;             PG8_LDB(B0, 1, 0); PG8_LDB(B1, 1, 1); PG8_SCHED; PG8_LDA(At, 1, 0); PG8_STAGE(PG8_SA(0, 1), a2 + hstep, voffA);
;             PG8_WAIT_V(8); PG8_WAIT_L(0); PG8_BAR; PG8_MMA(0, 0, At, B0); PG8_MMA(0, 1, At, B1); PG8_BAR; PG8_SCHED;
	s_waitcnt lgkmcnt(0)
	v_mfma_f32_16x16x32_bf16 v[60:63], v[152:155], v[184:187], v[60:63]
	v_mfma_f32_16x16x32_bf16 v[52:55], v[160:163], v[184:187], v[52:55]
	v_mfma_f32_16x16x32_bf16 v[44:47], v[152:155], v[192:195], v[44:47]
	v_mfma_f32_16x16x32_bf16 v[36:39], v[160:163], v[192:195], v[36:39]
	v_mfma_f32_16x16x32_bf16 v[28:31], v[152:155], v[204:207], v[28:31]
	v_mfma_f32_16x16x32_bf16 v[20:23], v[160:163], v[204:207], v[20:23]
	v_mfma_f32_16x16x32_bf16 v[12:15], v[152:155], v[212:215], v[12:15]
	v_mfma_f32_16x16x32_bf16 v[4:7], v[160:163], v[212:215], v[4:7]
	v_mfma_f32_16x16x32_bf16 v[60:63], v[156:159], v[188:191], v[60:63]
	v_mfma_f32_16x16x32_bf16 v[52:55], v[164:167], v[188:191], v[52:55]
	v_mfma_f32_16x16x32_bf16 v[44:47], v[156:159], v[196:199], v[44:47]
	v_mfma_f32_16x16x32_bf16 v[36:39], v[164:167], v[196:199], v[36:39]
	v_mfma_f32_16x16x32_bf16 v[28:31], v[156:159], v[208:211], v[28:31]
	v_mfma_f32_16x16x32_bf16 v[20:23], v[164:167], v[208:211], v[20:23]
	v_mfma_f32_16x16x32_bf16 v[12:15], v[156:159], v[216:219], v[12:15]
	v_mfma_f32_16x16x32_bf16 v[4:7], v[164:167], v[216:219], v[4:7]
	v_mfma_f32_16x16x32_bf16 v[56:59], v[168:171], v[184:187], v[56:59]
	v_mfma_f32_16x16x32_bf16 v[48:51], v[176:179], v[184:187], v[48:51]
	v_mfma_f32_16x16x32_bf16 v[40:43], v[168:171], v[192:195], v[40:43]
	v_mfma_f32_16x16x32_bf16 v[32:35], v[176:179], v[192:195], v[32:35]
	v_mfma_f32_16x16x32_bf16 v[24:27], v[168:171], v[204:207], v[24:27]
	v_mfma_f32_16x16x32_bf16 v[16:19], v[176:179], v[204:207], v[16:19]
	v_mfma_f32_16x16x32_bf16 v[8:11], v[168:171], v[212:215], v[8:11]
	v_mfma_f32_16x16x32_bf16 v[0:3], v[176:179], v[212:215], v[0:3]
	v_mfma_f32_16x16x32_bf16 v[56:59], v[172:175], v[188:191], v[56:59]
	v_mfma_f32_16x16x32_bf16 v[48:51], v[180:183], v[188:191], v[48:51]
	v_mfma_f32_16x16x32_bf16 v[40:43], v[172:175], v[196:199], v[40:43]
	v_mfma_f32_16x16x32_bf16 v[32:35], v[180:183], v[196:199], v[32:35]
	v_mfma_f32_16x16x32_bf16 v[24:27], v[172:175], v[208:211], v[24:27]
	v_mfma_f32_16x16x32_bf16 v[16:19], v[180:183], v[208:211], v[16:19]
	v_mfma_f32_16x16x32_bf16 v[8:11], v[172:175], v[216:219], v[8:11]
	v_mfma_f32_16x16x32_bf16 v[0:3], v[180:183], v[216:219], v[0:3]
	s_barrier
	s_add_i32 s46, 0, 0x18000
	v_add_u32_e32 v151, s46, v145
	s_add_i32 s47, 0, 0x1c000
	ds_read_b128 v[152:155], v151
	ds_read_b128 v[156:159], v151 offset:1024
	ds_read_b128 v[160:163], v151 offset:2048
	ds_read_b128 v[164:167], v151 offset:3072
	v_add_u32_e32 v151, s47, v145
	ds_read_b128 v[168:171], v151
	ds_read_b128 v[172:175], v151 offset:1024
	ds_read_b128 v[176:179], v151 offset:2048
	ds_read_b128 v[180:183], v151 offset:3072
	s_add_u32 s28, s28, 0x80000
	s_addc_u32 s29, s29, 0
	s_mov_b32 m0, s39
	v_lshl_add_u64 v[224:225], s[28:29], 0, v[128:129]
	ds_read_b128 v[184:187], v149 offset:32768
	ds_read_b128 v[188:191], v149 offset:33792
	ds_read_b128 v[192:195], v149 offset:34816
	ds_read_b128 v[196:199], v149 offset:35840
	ds_read_b128 v[204:207], v149 offset:36864
	ds_read_b128 v[208:211], v149 offset:37888
	ds_read_b128 v[212:215], v149 offset:38912
	ds_read_b128 v[216:219], v149 offset:39936
	global_load_lds_dwordx4 v[224:225], off
	s_mov_b32 m0, s40
	v_lshl_add_u64 v[224:225], s[28:29], 0, v[132:133]
	global_load_lds_dwordx4 v[224:225], off
	s_waitcnt vmcnt(8)
	s_waitcnt lgkmcnt(0)
	s_barrier
	s_waitcnt lgkmcnt(0)
	v_mfma_f32_16x16x32_bf16 v[112:115], v[152:155], v[184:187], v[112:115]
	v_mfma_f32_16x16x32_bf16 v[108:111], v[160:163], v[184:187], v[108:111]
	v_mfma_f32_16x16x32_bf16 v[100:103], v[152:155], v[192:195], v[100:103]
	v_mfma_f32_16x16x32_bf16 v[96:99], v[160:163], v[192:195], v[96:99]
	v_mfma_f32_16x16x32_bf16 v[92:95], v[152:155], v[204:207], v[92:95]
	v_mfma_f32_16x16x32_bf16 v[84:87], v[160:163], v[204:207], v[84:87]
	v_mfma_f32_16x16x32_bf16 v[76:79], v[152:155], v[212:215], v[76:79]
	v_mfma_f32_16x16x32_bf16 v[68:71], v[160:163], v[212:215], v[68:71]
	v_mfma_f32_16x16x32_bf16 v[112:115], v[156:159], v[188:191], v[112:115]
	v_mfma_f32_16x16x32_bf16 v[108:111], v[164:167], v[188:191], v[108:111]
	v_mfma_f32_16x16x32_bf16 v[100:103], v[156:159], v[196:199], v[100:103]
	v_mfma_f32_16x16x32_bf16 v[96:99], v[164:167], v[196:199], v[96:99]
	v_mfma_f32_16x16x32_bf16 v[92:95], v[156:159], v[208:211], v[92:95]
	v_mfma_f32_16x16x32_bf16 v[84:87], v[164:167], v[208:211], v[84:87]
	v_mfma_f32_16x16x32_bf16 v[76:79], v[156:159], v[216:219], v[76:79]
	v_mfma_f32_16x16x32_bf16 v[68:71], v[164:167], v[216:219], v[68:71]
	v_mfma_f32_16x16x32_bf16 v[124:127], v[168:171], v[184:187], v[124:127]
	v_mfma_f32_16x16x32_bf16 v[120:123], v[176:179], v[184:187], v[120:123]
	v_mfma_f32_16x16x32_bf16 v[116:119], v[168:171], v[192:195], v[116:119]
	v_mfma_f32_16x16x32_bf16 v[104:107], v[176:179], v[192:195], v[104:107]
	v_mfma_f32_16x16x32_bf16 v[88:91], v[168:171], v[204:207], v[88:91]
	v_mfma_f32_16x16x32_bf16 v[80:83], v[176:179], v[204:207], v[80:83]
	v_mfma_f32_16x16x32_bf16 v[72:75], v[168:171], v[212:215], v[72:75]
	v_mfma_f32_16x16x32_bf16 v[64:67], v[176:179], v[212:215], v[64:67]
	v_mfma_f32_16x16x32_bf16 v[124:127], v[172:175], v[188:191], v[124:127]
	v_mfma_f32_16x16x32_bf16 v[120:123], v[180:183], v[188:191], v[120:123]
	v_mfma_f32_16x16x32_bf16 v[116:119], v[172:175], v[196:199], v[116:119]
	v_mfma_f32_16x16x32_bf16 v[104:107], v[180:183], v[196:199], v[104:107]
	v_mfma_f32_16x16x32_bf16 v[88:91], v[172:175], v[208:211], v[88:91]
	v_mfma_f32_16x16x32_bf16 v[80:83], v[180:183], v[208:211], v[80:83]
	v_mfma_f32_16x16x32_bf16 v[72:75], v[172:175], v[216:219], v[72:75]
	v_mfma_f32_16x16x32_bf16 v[64:67], v[180:183], v[216:219], v[64:67]
	s_barrier
; #define PG8_STAGE(bufoff, gbase, voff) do { _Pragma("unroll") for (int _i = 0; _i < 2; ++_i) \
;         __builtin_amdgcn_global_load_lds((const unsigned*)((const char*)(gbase) + (voff)[_i]), (LAS unsigned*)(lds + (bufoff) + ldsw + _i * 8192), 16, 0, 0); } while (0)
; #define PG8_LDA(dst, b, h) do { _Pragma("unroll") for (int m = 0; m < 4; ++m) _Pragma("unroll") for (int k = 0; k < 2; ++k) dst[m][k] = *(const LAS bf16x8*)(lds + PG8_SA(b, h) + aoff + m * 2048 + k * 1024); } while (0)
; #define PG8_MMA(ai, bj, At, Bt) do { __builtin_amdgcn_s_setprio(1); _Pragma("unroll") for (int m = 0; m < 4; ++m) _Pragma("unroll") for (int n = 0; n < 2; ++n) _Pragma("unroll") for (int k = 0; k < 2; ++k) \
;         acc[ai][bj][m][n] = __builtin_amdgcn_mfma_f32_16x16x32_bf16(Bt[n][k], At[m][k], acc[ai][bj][m][n], 0, 0, 0); __builtin_amdgcn_s_setprio(0); } while (0)
; #define PG8_WAIT_V(n) asm volatile("s_waitcnt vmcnt(" #n ")" ::: "memory")
; #define PG8_WAIT_L(n) asm volatile("s_waitcnt lgkmcnt(" #n ")" ::: "memory")
; #define PG8_BAR __builtin_amdgcn_s_barrier()
; #define PG8_SCHED __builtin_amdgcn_sched_barrier(0)
; template <class Epi, class Sched, bool ALIGN_EPI = true>
; __device__ __forceinline__ void gemm_phase(LAS unsigned char* lds, const Gemm g, const Sched& S, const Epi& E) {
;     ...
;             PG8_LDA(At, 1, 1); PG8_STAGE(PG8_SB(1, 0), b3, voffB); PG8_STAGE(PG8_SB(1, 1), b3 + hstep, voffB); PG8_STAGE(PG8_SA(1, 0), a3, voffA);
;             PG8_WAIT_V(8); PG8_WAIT_L(0); PG8_BAR; PG8_MMA(1, 0, At, B0); PG8_MMA(1, 1, At, B1); PG8_BAR; PG8_SCHED;
;         }
;         if constexpr (ALIGN_EPI) { if (wr == 0) PG8_BAR; }
	s_add_i32 s28, s46, s36
	v_lshl_add_u64 v[140:141], v[140:141], 0, s[18:19]
	s_mov_b32 m0, s28
	ds_read_b128 v[184:187], v149 offset:49152
	ds_read_b128 v[188:191], v149 offset:50176
	ds_read_b128 v[192:195], v149 offset:51200
	ds_read_b128 v[196:199], v149 offset:52224
	ds_read_b128 v[204:207], v149 offset:53248
	ds_read_b128 v[208:211], v149 offset:54272
	ds_read_b128 v[212:215], v149 offset:55296
	ds_read_b128 v[216:219], v149 offset:56320
	global_load_lds_dwordx4 v[140:141], off
	s_add_i32 m0, s28, 0x2000
	s_add_u32 s26, s26, 0x80080
	v_lshl_add_u64 v[140:141], v[200:201], 0, s[18:19]
	s_addc_u32 s27, s27, 0
	s_add_i32 s28, s47, s36
	global_load_lds_dwordx4 v[140:141], off
	s_mov_b32 m0, s28
	s_nop 0
	global_load_lds_dwordx4 v130, s[26:27]
	s_add_i32 m0, s28, 0x2000
	s_nop 0
	global_load_lds_dwordx4 v134, s[26:27]
	s_mov_b32 m0, s41
	v_lshl_add_u64 v[140:141], v[220:221], 0, s[18:19]
	global_load_lds_dwordx4 v[140:141], off
	s_mov_b32 m0, s42
	v_lshl_add_u64 v[140:141], v[222:223], 0, s[18:19]
	global_load_lds_dwordx4 v[140:141], off
	s_waitcnt vmcnt(8)
	s_waitcnt lgkmcnt(0)
	s_barrier
	s_waitcnt lgkmcnt(0)
	v_mfma_f32_16x16x32_bf16 v[60:63], v[152:155], v[184:187], v[60:63]
	v_mfma_f32_16x16x32_bf16 v[52:55], v[160:163], v[184:187], v[52:55]
	v_mfma_f32_16x16x32_bf16 v[44:47], v[152:155], v[192:195], v[44:47]
	v_mfma_f32_16x16x32_bf16 v[36:39], v[160:163], v[192:195], v[36:39]
	v_mfma_f32_16x16x32_bf16 v[28:31], v[152:155], v[204:207], v[28:31]
	v_mfma_f32_16x16x32_bf16 v[20:23], v[160:163], v[204:207], v[20:23]
	v_mfma_f32_16x16x32_bf16 v[12:15], v[152:155], v[212:215], v[12:15]
	v_mfma_f32_16x16x32_bf16 v[4:7], v[160:163], v[212:215], v[4:7]
	v_mfma_f32_16x16x32_bf16 v[60:63], v[156:159], v[188:191], v[60:63]
	v_mfma_f32_16x16x32_bf16 v[52:55], v[164:167], v[188:191], v[52:55]
	v_mfma_f32_16x16x32_bf16 v[44:47], v[156:159], v[196:199], v[44:47]
	v_mfma_f32_16x16x32_bf16 v[36:39], v[164:167], v[196:199], v[36:39]
	v_mfma_f32_16x16x32_bf16 v[28:31], v[156:159], v[208:211], v[28:31]
	v_mfma_f32_16x16x32_bf16 v[20:23], v[164:167], v[208:211], v[20:23]
	v_mfma_f32_16x16x32_bf16 v[12:15], v[156:159], v[216:219], v[12:15]
	v_mfma_f32_16x16x32_bf16 v[4:7], v[164:167], v[216:219], v[4:7]
	v_mfma_f32_16x16x32_bf16 v[56:59], v[168:171], v[184:187], v[56:59]
	v_mfma_f32_16x16x32_bf16 v[48:51], v[176:179], v[184:187], v[48:51]
	v_mfma_f32_16x16x32_bf16 v[40:43], v[168:171], v[192:195], v[40:43]
	v_mfma_f32_16x16x32_bf16 v[32:35], v[176:179], v[192:195], v[32:35]
	v_mfma_f32_16x16x32_bf16 v[24:27], v[168:171], v[204:207], v[24:27]
	v_mfma_f32_16x16x32_bf16 v[16:19], v[176:179], v[204:207], v[16:19]
	v_mfma_f32_16x16x32_bf16 v[8:11], v[168:171], v[212:215], v[8:11]
	v_mfma_f32_16x16x32_bf16 v[0:3], v[176:179], v[212:215], v[0:3]
	v_mfma_f32_16x16x32_bf16 v[56:59], v[172:175], v[188:191], v[56:59]
	v_mfma_f32_16x16x32_bf16 v[48:51], v[180:183], v[188:191], v[48:51]
	v_mfma_f32_16x16x32_bf16 v[40:43], v[172:175], v[196:199], v[40:43]
	v_mfma_f32_16x16x32_bf16 v[32:35], v[180:183], v[196:199], v[32:35]
	v_mfma_f32_16x16x32_bf16 v[24:27], v[172:175], v[208:211], v[24:27]
	v_mfma_f32_16x16x32_bf16 v[16:19], v[180:183], v[208:211], v[16:19]
	v_mfma_f32_16x16x32_bf16 v[8:11], v[172:175], v[216:219], v[8:11]
	v_mfma_f32_16x16x32_bf16 v[0:3], v[180:183], v[216:219], v[0:3]
	s_barrier
	s_add_i32 s56, s56, 2
	s_add_u32 s24, s24, 0x100
	s_addc_u32 s25, s25, 0
	s_add_u32 s54, s54, 0x100
	s_addc_u32 s55, s55, 0
	s_cmp_gt_u32 s56, 29
	s_cbranch_scc0 .LBB0_647
	s_and_b64 vcc, exec, s[20:21]
	s_cbranch_vccz .LBB0_650
	s_barrier

; #define PG8_STAGE(bufoff, gbase, voff) do { _Pragma("unroll") for (int _i = 0; _i < 2; ++_i) \
;         __builtin_amdgcn_global_load_lds((const unsigned*)((const char*)(gbase) + (voff)[_i]), (LAS unsigned*)(lds + (bufoff) + ldsw + _i * 8192), 16, 0, 0); } while (0)
; #define PG8_WAIT_V(n) asm volatile("s_waitcnt vmcnt(" #n ")" ::: "memory")
; #define PG8_BAR __builtin_amdgcn_s_barrier()
; template <class Epi, class Sched, bool ALIGN_EPI = true>
; __device__ __forceinline__ void gemm_phase(LAS unsigned char* lds, const Gemm g, const Sched& S, const Epi& E) {
;     ...
;     PG8_WAIT_V(2); PG8_BAR;
;     PG8_STAGE(PG8_SB(1, 0), cB + kstep, voffB); PG8_STAGE(PG8_SA(1, 0), cA + kstep, voffA); PG8_STAGE(PG8_SB(1, 1), cB + hstep + kstep, voffB);
;     PG8_WAIT_V(6); PG8_BAR;
.LBB0_664:
	s_add_u32 s10, s68, 0x24500000
	s_addc_u32 s11, s69, 0
	s_lshl_b32 s5, s5, 5
	s_mov_b64 s[12:13], 0x80
	s_and_b32 s18, s5, 0x60
	s_add_i32 m0, s23, 0x18000
	v_lshl_add_u64 v[6:7], v[6:7], 0, s[12:13]
	s_lshl_b32 s15, s4, 13
	s_lshl_b32 s5, s18, 7
	s_waitcnt vmcnt(2)
	s_barrier
	global_load_lds_dwordx4 v[6:7], off
	v_lshl_add_u64 v[4:5], v[4:5], 0, s[12:13]
	s_add_i32 m0, s23, 0x1a000
	s_add_i32 s57, s23, 0x8000
	s_add_i32 s58, s23, 0xa000
	global_load_lds_dwordx4 v[4:5], off
	v_lshl_add_u64 v[0:1], v[0:1], 0, s[12:13]
	s_mov_b32 m0, s57
	s_add_u32 s16, s6, 0x10080
	global_load_lds_dwordx4 v[0:1], off
	v_lshl_add_u64 v[0:1], v[2:3], 0, s[12:13]
	s_mov_b32 m0, s58
	s_addc_u32 s17, s7, 0
	global_load_lds_dwordx4 v[0:1], off
	s_add_i32 m0, s23, 0x1c000
	s_nop 0
	global_load_lds_dwordx4 v130, s[16:17]
	v_lshl_add_u64 v[0:1], s[16:17], 0, v[134:135]
	s_add_i32 m0, s23, 0x1e000
	s_cmpk_lt_u32 s14, 0x100
	global_load_lds_dwordx4 v[0:1], off
	v_lshrrev_b32_e32 v1, 1, v8
	v_and_b32_e32 v1, 24, v1
	v_and_b32_e32 v0, 15, v8
	v_lshlrev_b32_e32 v2, 1, v1
	v_lshl_or_b32 v138, s4, 6, v0
	v_lshl_or_b32 v0, v0, 6, v2
	v_lshlrev_b32_e32 v2, 2, v8
	v_and_b32_e32 v2, 32, v2
	v_bitop3_b32 v3, v0, s15, v2 bitop3:0xde
	v_bitop3_b32 v0, v0, s5, v2 bitop3:0xde
	s_waitcnt vmcnt(6)
	s_cselect_b64 s[4:5], -1, 0
	s_add_i32 s61, 0, 0x10000
	s_add_i32 s63, 0, 0x14000
	s_add_i32 s77, 0, 0x18000
	s_add_i32 s79, 0, 0x1c000
	v_add_u32_e32 v140, s61, v0
	v_add_u32_e32 v141, s63, v0
	s_add_i32 s61, s61, s24
	s_add_i32 s63, s63, s24
	v_add_u32_e32 v143, s77, v0
	v_add_u32_e32 v144, s79, v0
	s_add_i32 s77, s77, s24
	s_add_i32 s79, s79, s24
	v_cndmask_b32_e64 v0, 0, 1, s[4:5]
	s_mov_b32 s15, 0
	v_or_b32_e32 v139, s18, v1
	v_add_u32_e32 v142, 0, v3
	s_add_i32 s59, s23, 0xc000
	s_add_i32 s60, s23, 0xe000
	s_mov_b64 s[16:17], 0x100
	s_add_i32 s62, s61, 0x2000
	s_add_i32 s76, s63, 0x2000
	s_mov_b64 s[18:19], 0x180
	s_add_i32 s78, s77, 0x2000
	s_add_i32 s80, s79, 0x2000
	v_cmp_ne_u32_e64 s[4:5], 1, v0
	s_mov_b64 s[24:25], 0x80000
	s_mov_b32 s81, 0x80000
	s_mov_b64 s[26:27], 0x90000
	s_mov_b32 s83, 0x90000
	s_mov_b64 s[28:29], 0xa0000
	s_mov_b32 s84, 0xa0000
	s_mov_b64 s[30:31], 0xb0000
	s_mov_b32 s85, 0xb0000
	s_barrier
	s_branch .LBB0_667

; #define PG8_STAGE(bufoff, gbase, voff) do { _Pragma("unroll") for (int _i = 0; _i < 2; ++_i) \
;         __builtin_amdgcn_global_load_lds((const unsigned*)((const char*)(gbase) + (voff)[_i]), (LAS unsigned*)(lds + (bufoff) + ldsw + _i * 8192), 16, 0, 0); } while (0)
; #define PG8_LDA(dst, b, h) do { _Pragma("unroll") for (int m = 0; m < 4; ++m) _Pragma("unroll") for (int k = 0; k < 2; ++k) dst[m][k] = *(const LAS bf16x8*)(lds + PG8_SA(b, h) + aoff + m * 2048 + k * 1024); } while (0)
; #define PG8_LDB(dst, b, h) do { _Pragma("unroll") for (int n = 0; n < 2; ++n) _Pragma("unroll") for (int k = 0; k < 2; ++k) dst[n][k] = *(const LAS bf16x8*)(lds + PG8_SB(b, h) + boff + n * 2048 + k * 1024); } while (0)
; #define PG8_MMA(ai, bj, At, Bt) do { __builtin_amdgcn_s_setprio(1); _Pragma("unroll") for (int m = 0; m < 4; ++m) _Pragma("unroll") for (int n = 0; n < 2; ++n) _Pragma("unroll") for (int k = 0; k < 2; ++k) \
;         acc[ai][bj][m][n] = __builtin_amdgcn_mfma_f32_16x16x32_bf16(Bt[n][k], At[m][k], acc[ai][bj][m][n], 0, 0, 0); __builtin_amdgcn_s_setprio(0); } while (0)
; #define PG8_BAR __builtin_amdgcn_s_barrier()
; template <class Epi, class Sched, bool ALIGN_EPI = true>
; __device__ __forceinline__ void gemm_phase(LAS unsigned char* lds, const Gemm g, const Sched& S, const Epi& E) {
;     ...
;         const bool has_next = PG8_NEXT(ui + 1, nxt);
;         const char* nA = has_next ? (const char*)g.A + (size_t)nxt.pm * tstep : cA; const char* nB = has_next ? (const char*)g.Bt + (size_t)nxt.pn * tstep : cB;
;         for (int t = 0; t < nt; t += 2) {
;             const bool last = (t == nt - 2);
;             const char* a1 = cA + (size_t)(t + 1) * kstep;
;             const char* a2 = last ? nA : cA + (size_t)(t + 2) * kstep; const char* b2 = last ? nB : cB + (size_t)(t + 2) * kstep;
;             const char* a3 = a2 + kstep; const char* b3 = b2 + kstep;
;             PG8_LDB(B0, 0, 0); PG8_LDB(B1, 0, 1); PG8_SCHED; PG8_LDA(At, 0, 0); PG8_STAGE(PG8_SA(1, 1), a1 + hstep, voffA);
;             PG8_WAIT_V(8); PG8_WAIT_L(0); PG8_BAR; PG8_MMA(0, 0, At, B0); PG8_MMA(0, 1, At, B1); PG8_BAR; PG8_SCHED;
;             PG8_LDA(At, 0, 1); PG8_STAGE(PG8_SB(0, 0), b2, voffB); PG8_STAGE(PG8_SB(0, 1), b2 + hstep, voffB); PG8_STAGE(PG8_SA(0, 0), a2, voffA);
;             PG8_WAIT_V(8); PG8_WAIT_L(0); PG8_BAR; PG8_MMA(1, 0, At, B0); PG8_MMA(1, 1, At, B1); PG8_BAR; PG8_SCHED;
.LBB0_667:
	v_readlane_b32 s14, v137, s56
	ds_read_b128 v[0:3], v140
	ds_read_b128 v[4:7], v140 offset:1024
	ds_read_b128 v[8:11], v140 offset:2048
	ds_read_b128 v[12:15], v140 offset:3072
	ds_read_b128 v[16:19], v141
	ds_read_b128 v[20:23], v141 offset:1024
	ds_read_b128 v[24:27], v141 offset:2048
	ds_read_b128 v[28:31], v141 offset:3072
	s_cmp_gt_i32 s14, -1
	s_mov_b64 s[48:49], s[6:7]
	s_cselect_b64 s[38:39], -1, 0
	s_lshl_b64 s[6:7], s[14:15], 17
	s_add_u32 s36, s3, s6
	s_addc_u32 s37, s50, s7
	v_readlane_b32 s34, v136, s56
	s_and_b64 s[6:7], s[38:39], exec
	s_cselect_b32 s45, s37, s43
	s_cselect_b32 s44, s36, s42
	s_ashr_i32 s35, s34, 31
	s_lshl_b64 s[6:7], s[34:35], 17
	s_add_u32 s6, s51, s6
	s_addc_u32 s7, s52, s7
	s_and_b64 s[40:41], s[38:39], exec
	s_cselect_b32 s41, s7, s49
	s_cselect_b32 s40, s6, s48
	s_add_u32 s46, s42, 0x10080
	s_addc_u32 s47, s43, 0
	s_mov_b32 m0, s59
	v_lshl_add_u64 v[64:65], s[46:47], 0, v[128:129]
	ds_read_b128 v[32:35], v142
	ds_read_b128 v[36:39], v142 offset:1024
	ds_read_b128 v[40:43], v142 offset:2048
	ds_read_b128 v[44:47], v142 offset:3072
	ds_read_b128 v[48:51], v142 offset:4096
	ds_read_b128 v[52:55], v142 offset:5120
	ds_read_b128 v[56:59], v142 offset:6144
	ds_read_b128 v[60:63], v142 offset:7168
	global_load_lds_dwordx4 v[64:65], off
	s_mov_b32 m0, s60
	v_lshl_add_u64 v[64:65], s[46:47], 0, v[132:133]
	global_load_lds_dwordx4 v[64:65], off
	s_waitcnt vmcnt(8)
	s_waitcnt lgkmcnt(0)
	s_barrier
	s_waitcnt lgkmcnt(0)
	v_mfma_f32_16x16x32_bf16 v[64:67], v[0:3], v[32:35], 0
	v_mfma_f32_16x16x32_bf16 v[68:71], v[8:11], v[32:35], 0
	v_mfma_f32_16x16x32_bf16 v[72:75], v[0:3], v[40:43], 0
	v_mfma_f32_16x16x32_bf16 v[76:79], v[8:11], v[40:43], 0
	v_mfma_f32_16x16x32_bf16 v[80:83], v[0:3], v[48:51], 0
	v_mfma_f32_16x16x32_bf16 v[84:87], v[8:11], v[48:51], 0
	v_mfma_f32_16x16x32_bf16 v[88:91], v[0:3], v[56:59], 0
	v_mfma_f32_16x16x32_bf16 v[92:95], v[8:11], v[56:59], 0
	v_mfma_f32_16x16x32_bf16 v[64:67], v[4:7], v[36:39], v[64:67]
	v_mfma_f32_16x16x32_bf16 v[68:71], v[12:15], v[36:39], v[68:71]
	v_mfma_f32_16x16x32_bf16 v[72:75], v[4:7], v[44:47], v[72:75]
	v_mfma_f32_16x16x32_bf16 v[76:79], v[12:15], v[44:47], v[76:79]
	v_mfma_f32_16x16x32_bf16 v[80:83], v[4:7], v[52:55], v[80:83]
	v_mfma_f32_16x16x32_bf16 v[84:87], v[12:15], v[52:55], v[84:87]
	v_mfma_f32_16x16x32_bf16 v[88:91], v[4:7], v[60:63], v[88:91]
	v_mfma_f32_16x16x32_bf16 v[92:95], v[12:15], v[60:63], v[92:95]
	v_mfma_f32_16x16x32_bf16 v[96:99], v[16:19], v[32:35], 0
	v_mfma_f32_16x16x32_bf16 v[32:35], v[24:27], v[32:35], 0
	v_mfma_f32_16x16x32_bf16 v[96:99], v[20:23], v[36:39], v[96:99]
	v_mfma_f32_16x16x32_bf16 v[32:35], v[28:31], v[36:39], v[32:35]
	v_mfma_f32_16x16x32_bf16 v[36:39], v[16:19], v[40:43], 0
	v_mfma_f32_16x16x32_bf16 v[40:43], v[24:27], v[40:43], 0
	v_mfma_f32_16x16x32_bf16 v[36:39], v[20:23], v[44:47], v[36:39]
	v_mfma_f32_16x16x32_bf16 v[40:43], v[28:31], v[44:47], v[40:43]
	v_mfma_f32_16x16x32_bf16 v[44:47], v[16:19], v[48:51], 0
	v_mfma_f32_16x16x32_bf16 v[48:51], v[24:27], v[48:51], 0
	v_mfma_f32_16x16x32_bf16 v[44:47], v[20:23], v[52:55], v[44:47]
	v_mfma_f32_16x16x32_bf16 v[48:51], v[28:31], v[52:55], v[48:51]
	v_mfma_f32_16x16x32_bf16 v[52:55], v[16:19], v[56:59], 0
	v_mfma_f32_16x16x32_bf16 v[56:59], v[24:27], v[56:59], 0
	v_mfma_f32_16x16x32_bf16 v[52:55], v[20:23], v[60:63], v[52:55]
	v_mfma_f32_16x16x32_bf16 v[56:59], v[28:31], v[60:63], v[56:59]
	s_barrier
	v_lshl_add_u64 v[212:213], s[48:49], 0, v[130:131]
	s_mov_b32 m0, s61
	v_lshl_add_u64 v[146:147], v[212:213], 0, s[16:17]
	v_lshl_add_u64 v[214:215], s[48:49], 0, v[134:135]
	s_add_u32 s46, s48, 0x10100
	ds_read_b128 v[60:63], v142 offset:16384
	ds_read_b128 v[100:103], v142 offset:17408
	ds_read_b128 v[104:107], v142 offset:18432
	ds_read_b128 v[108:111], v142 offset:19456
	ds_read_b128 v[112:115], v142 offset:20480
	ds_read_b128 v[116:119], v142 offset:21504
	ds_read_b128 v[120:123], v142 offset:22528
	ds_read_b128 v[124:127], v142 offset:23552
	global_load_lds_dwordx4 v[146:147], off
	v_lshl_add_u64 v[146:147], v[214:215], 0, s[16:17]
	s_mov_b32 m0, s62
	s_addc_u32 s47, s49, 0
	global_load_lds_dwordx4 v[146:147], off
	v_lshl_add_u64 v[146:147], s[46:47], 0, v[130:131]
	s_mov_b32 m0, s63
	v_lshl_add_u64 v[216:217], s[42:43], 0, v[128:129]
	global_load_lds_dwordx4 v[146:147], off
	v_lshl_add_u64 v[146:147], s[46:47], 0, v[134:135]
	s_mov_b32 m0, s76
	v_lshl_add_u64 v[218:219], s[42:43], 0, v[132:133]
	global_load_lds_dwordx4 v[146:147], off
	s_mov_b32 m0, s23
	v_lshl_add_u64 v[146:147], v[216:217], 0, s[16:17]
	global_load_lds_dwordx4 v[146:147], off
	s_mov_b32 m0, s53
	v_lshl_add_u64 v[146:147], v[218:219], 0, s[16:17]
	global_load_lds_dwordx4 v[146:147], off
	s_waitcnt vmcnt(8)
	s_waitcnt lgkmcnt(0)
	s_barrier
; #define PG8_STAGE(bufoff, gbase, voff) do { _Pragma("unroll") for (int _i = 0; _i < 2; ++_i) \
;         __builtin_amdgcn_global_load_lds((const unsigned*)((const char*)(gbase) + (voff)[_i]), (LAS unsigned*)(lds + (bufoff) + ldsw + _i * 8192), 16, 0, 0); } while (0)
; #define PG8_LDA(dst, b, h) do { _Pragma("unroll") for (int m = 0; m < 4; ++m) _Pragma("unroll") for (int k = 0; k < 2; ++k) dst[m][k] = *(const LAS bf16x8*)(lds + PG8_SA(b, h) + aoff + m * 2048 + k * 1024); } while (0)
; #define PG8_LDB(dst, b, h) do { _Pragma("unroll") for (int n = 0; n < 2; ++n) _Pragma("unroll") for (int k = 0; k < 2; ++k) dst[n][k] = *(const LAS bf16x8*)(lds + PG8_SB(b, h) + boff + n * 2048 + k * 1024); } while (0)
; #define PG8_MMA(ai, bj, At, Bt) do { __builtin_amdgcn_s_setprio(1); _Pragma("unroll") for (int m = 0; m < 4; ++m) _Pragma("unroll") for (int n = 0; n < 2; ++n) _Pragma("unroll") for (int k = 0; k < 2; ++k) \
;         acc[ai][bj][m][n] = __builtin_amdgcn_mfma_f32_16x16x32_bf16(Bt[n][k], At[m][k], acc[ai][bj][m][n], 0, 0, 0); __builtin_amdgcn_s_setprio(0); } while (0)
; #define PG8_WAIT_V(n) asm volatile("s_waitcnt vmcnt(" #n ")" ::: "memory")
; #define PG8_WAIT_L(n) asm volatile("s_waitcnt lgkmcnt(" #n ")" ::: "memory")
; #define PG8_BAR __builtin_amdgcn_s_barrier()
; #define PG8_SCHED __builtin_amdgcn_sched_barrier(0)
; template <class Epi, class Sched, bool ALIGN_EPI = true>
; __device__ __forceinline__ void gemm_phase(LAS unsigned char* lds, const Gemm g, const Sched& S, const Epi& E) {
;     ...
;             PG8_WAIT_V(8); PG8_WAIT_L(0); PG8_BAR; PG8_MMA(1, 0, At, B0); PG8_MMA(1, 1, At, B1); PG8_BAR; PG8_SCHED;
;             PG8_LDB(B0, 1, 0); PG8_LDB(B1, 1, 1); PG8_SCHED; PG8_LDA(At, 1, 0); PG8_STAGE(PG8_SA(0, 1), a2 + hstep, voffA);
;             PG8_WAIT_V(8); PG8_WAIT_L(0); PG8_BAR; PG8_MMA(0, 0, At, B0); PG8_MMA(0, 1, At, B1); PG8_BAR; PG8_SCHED;
	s_waitcnt lgkmcnt(0)
	v_mfma_f32_16x16x32_bf16 v[146:149], v[0:3], v[60:63], 0
	v_mfma_f32_16x16x32_bf16 v[154:157], v[0:3], v[104:107], 0
	v_mfma_f32_16x16x32_bf16 v[162:165], v[0:3], v[112:115], 0
	v_mfma_f32_16x16x32_bf16 v[0:3], v[0:3], v[120:123], 0
	v_mfma_f32_16x16x32_bf16 v[146:149], v[4:7], v[100:103], v[146:149]
	v_mfma_f32_16x16x32_bf16 v[154:157], v[4:7], v[108:111], v[154:157]
	v_mfma_f32_16x16x32_bf16 v[162:165], v[4:7], v[116:119], v[162:165]
	v_mfma_f32_16x16x32_bf16 v[0:3], v[4:7], v[124:127], v[0:3]
	v_mfma_f32_16x16x32_bf16 v[4:7], v[8:11], v[120:123], 0
	v_mfma_f32_16x16x32_bf16 v[150:153], v[8:11], v[60:63], 0
	v_mfma_f32_16x16x32_bf16 v[158:161], v[8:11], v[104:107], 0
	v_mfma_f32_16x16x32_bf16 v[166:169], v[8:11], v[112:115], 0
	v_mfma_f32_16x16x32_bf16 v[4:7], v[12:15], v[124:127], v[4:7]
	v_mfma_f32_16x16x32_bf16 v[150:153], v[12:15], v[100:103], v[150:153]
	v_mfma_f32_16x16x32_bf16 v[158:161], v[12:15], v[108:111], v[158:161]
	v_mfma_f32_16x16x32_bf16 v[166:169], v[12:15], v[116:119], v[166:169]
	v_mfma_f32_16x16x32_bf16 v[8:11], v[16:19], v[60:63], 0
	v_mfma_f32_16x16x32_bf16 v[12:15], v[24:27], v[60:63], 0
	v_mfma_f32_16x16x32_bf16 v[8:11], v[20:23], v[100:103], v[8:11]
	v_mfma_f32_16x16x32_bf16 v[12:15], v[28:31], v[100:103], v[12:15]
	v_mfma_f32_16x16x32_bf16 v[60:63], v[16:19], v[104:107], 0
	v_mfma_f32_16x16x32_bf16 v[100:103], v[24:27], v[104:107], 0
	v_mfma_f32_16x16x32_bf16 v[104:107], v[16:19], v[112:115], 0
	v_mfma_f32_16x16x32_bf16 v[16:19], v[16:19], v[120:123], 0
	v_mfma_f32_16x16x32_bf16 v[60:63], v[20:23], v[108:111], v[60:63]
	v_mfma_f32_16x16x32_bf16 v[100:103], v[28:31], v[108:111], v[100:103]
	v_mfma_f32_16x16x32_bf16 v[104:107], v[20:23], v[116:119], v[104:107]
	v_mfma_f32_16x16x32_bf16 v[108:111], v[24:27], v[112:115], 0
	v_mfma_f32_16x16x32_bf16 v[16:19], v[20:23], v[124:127], v[16:19]
	v_mfma_f32_16x16x32_bf16 v[20:23], v[24:27], v[120:123], 0
	v_mfma_f32_16x16x32_bf16 v[108:111], v[28:31], v[116:119], v[108:111]
	v_mfma_f32_16x16x32_bf16 v[20:23], v[28:31], v[124:127], v[20:23]
	s_barrier
	ds_read_b128 v[24:27], v143
	ds_read_b128 v[28:31], v143 offset:1024
	ds_read_b128 v[112:115], v143 offset:2048
	ds_read_b128 v[116:119], v143 offset:3072
	ds_read_b128 v[120:123], v144
	ds_read_b128 v[124:127], v144 offset:1024
	ds_read_b128 v[170:173], v144 offset:2048
	ds_read_b128 v[174:177], v144 offset:3072
	s_add_u32 s46, s42, 0x10100
	s_addc_u32 s47, s43, 0
	s_mov_b32 m0, s54
	v_lshl_add_u64 v[220:221], s[46:47], 0, v[128:129]
	ds_read_b128 v[178:181], v142 offset:32768
	ds_read_b128 v[182:185], v142 offset:33792
	ds_read_b128 v[186:189], v142 offset:34816
	ds_read_b128 v[190:193], v142 offset:35840
	ds_read_b128 v[194:197], v142 offset:36864
	ds_read_b128 v[198:201], v142 offset:37888
	ds_read_b128 v[204:207], v142 offset:38912
	ds_read_b128 v[208:211], v142 offset:39936
	global_load_lds_dwordx4 v[220:221], off
	s_mov_b32 m0, s55
	s_nop 0
	global_load_lds_dwordx4 v132, s[46:47]
	s_waitcnt vmcnt(8)
	s_waitcnt lgkmcnt(0)
	s_barrier
	s_waitcnt lgkmcnt(0)
	v_mfma_f32_16x16x32_bf16 v[64:67], v[24:27], v[178:181], v[64:67]
	v_mfma_f32_16x16x32_bf16 v[68:71], v[112:115], v[178:181], v[68:71]
	v_mfma_f32_16x16x32_bf16 v[72:75], v[24:27], v[186:189], v[72:75]
	v_mfma_f32_16x16x32_bf16 v[76:79], v[112:115], v[186:189], v[76:79]
	v_mfma_f32_16x16x32_bf16 v[80:83], v[24:27], v[194:197], v[80:83]
	v_mfma_f32_16x16x32_bf16 v[84:87], v[112:115], v[194:197], v[84:87]
	v_mfma_f32_16x16x32_bf16 v[88:91], v[24:27], v[204:207], v[88:91]
	v_mfma_f32_16x16x32_bf16 v[92:95], v[112:115], v[204:207], v[92:95]
	v_mfma_f32_16x16x32_bf16 v[64:67], v[28:31], v[182:185], v[64:67]
	v_mfma_f32_16x16x32_bf16 v[68:71], v[116:119], v[182:185], v[68:71]
	v_mfma_f32_16x16x32_bf16 v[72:75], v[28:31], v[190:193], v[72:75]
	v_mfma_f32_16x16x32_bf16 v[76:79], v[116:119], v[190:193], v[76:79]
	v_mfma_f32_16x16x32_bf16 v[80:83], v[28:31], v[198:201], v[80:83]
	v_mfma_f32_16x16x32_bf16 v[84:87], v[116:119], v[198:201], v[84:87]
	v_mfma_f32_16x16x32_bf16 v[88:91], v[28:31], v[208:211], v[88:91]
	v_mfma_f32_16x16x32_bf16 v[92:95], v[116:119], v[208:211], v[92:95]
	v_mfma_f32_16x16x32_bf16 v[96:99], v[120:123], v[178:181], v[96:99]
	v_mfma_f32_16x16x32_bf16 v[32:35], v[170:173], v[178:181], v[32:35]
	v_mfma_f32_16x16x32_bf16 v[36:39], v[120:123], v[186:189], v[36:39]
	v_mfma_f32_16x16x32_bf16 v[40:43], v[170:173], v[186:189], v[40:43]
	v_mfma_f32_16x16x32_bf16 v[44:47], v[120:123], v[194:197], v[44:47]
	v_mfma_f32_16x16x32_bf16 v[48:51], v[170:173], v[194:197], v[48:51]
	v_mfma_f32_16x16x32_bf16 v[52:55], v[120:123], v[204:207], v[52:55]
	v_mfma_f32_16x16x32_bf16 v[56:59], v[170:173], v[204:207], v[56:59]
	v_mfma_f32_16x16x32_bf16 v[96:99], v[124:127], v[182:185], v[96:99]
	v_mfma_f32_16x16x32_bf16 v[32:35], v[174:177], v[182:185], v[32:35]
	v_mfma_f32_16x16x32_bf16 v[36:39], v[124:127], v[190:193], v[36:39]
	v_mfma_f32_16x16x32_bf16 v[40:43], v[174:177], v[190:193], v[40:43]
	v_mfma_f32_16x16x32_bf16 v[44:47], v[124:127], v[198:201], v[44:47]
	v_mfma_f32_16x16x32_bf16 v[48:51], v[174:177], v[198:201], v[48:51]
	v_mfma_f32_16x16x32_bf16 v[52:55], v[124:127], v[208:211], v[52:55]
	v_mfma_f32_16x16x32_bf16 v[56:59], v[174:177], v[208:211], v[56:59]
	s_barrier
; #define PG8_STAGE(bufoff, gbase, voff) do { _Pragma("unroll") for (int _i = 0; _i < 2; ++_i) \
;         __builtin_amdgcn_global_load_lds((const unsigned*)((const char*)(gbase) + (voff)[_i]), (LAS unsigned*)(lds + (bufoff) + ldsw + _i * 8192), 16, 0, 0); } while (0)
; #define PG8_LDA(dst, b, h) do { _Pragma("unroll") for (int m = 0; m < 4; ++m) _Pragma("unroll") for (int k = 0; k < 2; ++k) dst[m][k] = *(const LAS bf16x8*)(lds + PG8_SA(b, h) + aoff + m * 2048 + k * 1024); } while (0)
; #define PG8_LDB(dst, b, h) do { _Pragma("unroll") for (int n = 0; n < 2; ++n) _Pragma("unroll") for (int k = 0; k < 2; ++k) dst[n][k] = *(const LAS bf16x8*)(lds + PG8_SB(b, h) + boff + n * 2048 + k * 1024); } while (0)
; #define PG8_MMA(ai, bj, At, Bt) do { __builtin_amdgcn_s_setprio(1); _Pragma("unroll") for (int m = 0; m < 4; ++m) _Pragma("unroll") for (int n = 0; n < 2; ++n) _Pragma("unroll") for (int k = 0; k < 2; ++k) \
;         acc[ai][bj][m][n] = __builtin_amdgcn_mfma_f32_16x16x32_bf16(Bt[n][k], At[m][k], acc[ai][bj][m][n], 0, 0, 0); __builtin_amdgcn_s_setprio(0); } while (0)
; #define PG8_WAIT_V(n) asm volatile("s_waitcnt vmcnt(" #n ")" ::: "memory")
; template <class Epi, class Sched, bool ALIGN_EPI = true>
; __device__ __forceinline__ void gemm_phase(LAS unsigned char* lds, const Gemm g, const Sched& S, const Epi& E) {
;     ...
;             PG8_LDB(B0, 0, 0); PG8_LDB(B1, 0, 1); PG8_SCHED; PG8_LDA(At, 0, 0); PG8_STAGE(PG8_SA(1, 1), a1 + hstep, voffA);
;             PG8_WAIT_V(8); PG8_WAIT_L(0); PG8_BAR; PG8_MMA(0, 0, At, B0); PG8_MMA(0, 1, At, B1); PG8_BAR; PG8_SCHED;
;             PG8_LDA(At, 0, 1); PG8_STAGE(PG8_SB(0, 0), b2, voffB); PG8_STAGE(PG8_SB(0, 1), b2 + hstep, voffB); PG8_STAGE(PG8_SA(0, 0), a2, voffA);
;             PG8_WAIT_V(8); PG8_WAIT_L(0); PG8_BAR; PG8_MMA(1, 0, At, B0); PG8_MMA(1, 1, At, B1); PG8_BAR; PG8_SCHED;
;             PG8_LDB(B0, 1, 0); PG8_LDB(B1, 1, 1); PG8_SCHED; PG8_LDA(At, 1, 0); PG8_STAGE(PG8_SA(0, 1), a2 + hstep, voffA);
;             PG8_WAIT_V(8); PG8_WAIT_L(0); PG8_BAR; PG8_MMA(0, 0, At, B0); PG8_MMA(0, 1, At, B1); PG8_BAR; PG8_SCHED;
;             PG8_LDA(At, 1, 1); PG8_STAGE(PG8_SB(1, 0), b3, voffB); PG8_STAGE(PG8_SB(1, 1), b3 + hstep, voffB); PG8_STAGE(PG8_SA(1, 0), a3, voffA);
;             PG8_WAIT_V(8); PG8_WAIT_L(0); PG8_BAR; PG8_MMA(1, 0, At, B0); PG8_MMA(1, 1, At, B1); PG8_BAR; PG8_SCHED;
	s_mov_b32 m0, s77
	v_lshl_add_u64 v[212:213], v[212:213], 0, s[18:19]
	s_add_u32 s46, s48, 0x10180
	ds_read_b128 v[178:181], v142 offset:49152
	ds_read_b128 v[182:185], v142 offset:50176
	ds_read_b128 v[186:189], v142 offset:51200
	ds_read_b128 v[190:193], v142 offset:52224
	ds_read_b128 v[194:197], v142 offset:53248
	ds_read_b128 v[198:201], v142 offset:54272
	ds_read_b128 v[204:207], v142 offset:55296
	ds_read_b128 v[208:211], v142 offset:56320
	global_load_lds_dwordx4 v[212:213], off
	v_lshl_add_u64 v[212:213], v[214:215], 0, s[18:19]
	s_mov_b32 m0, s78
	s_addc_u32 s47, s49, 0
	global_load_lds_dwordx4 v[212:213], off
	s_mov_b32 m0, s79
	s_nop 0
	global_load_lds_dwordx4 v130, s[46:47]
	s_mov_b32 m0, s80
	s_nop 0
	global_load_lds_dwordx4 v134, s[46:47]
	s_mov_b32 m0, s57
	v_lshl_add_u64 v[212:213], v[216:217], 0, s[18:19]
	global_load_lds_dwordx4 v[212:213], off
	s_mov_b32 m0, s58
	v_lshl_add_u64 v[212:213], v[218:219], 0, s[18:19]
	global_load_lds_dwordx4 v[212:213], off
	s_waitcnt vmcnt(8)
	s_waitcnt lgkmcnt(0)
	s_barrier
	s_waitcnt lgkmcnt(0)
	v_mfma_f32_16x16x32_bf16 v[0:3], v[24:27], v[204:207], v[0:3]
	v_mfma_f32_16x16x32_bf16 v[4:7], v[112:115], v[204:207], v[4:7]
	v_mfma_f32_16x16x32_bf16 v[146:149], v[24:27], v[178:181], v[146:149]
	v_mfma_f32_16x16x32_bf16 v[150:153], v[112:115], v[178:181], v[150:153]
	v_mfma_f32_16x16x32_bf16 v[154:157], v[24:27], v[186:189], v[154:157]
	v_mfma_f32_16x16x32_bf16 v[158:161], v[112:115], v[186:189], v[158:161]
	v_mfma_f32_16x16x32_bf16 v[162:165], v[24:27], v[194:197], v[162:165]
	v_mfma_f32_16x16x32_bf16 v[166:169], v[112:115], v[194:197], v[166:169]
	v_mfma_f32_16x16x32_bf16 v[0:3], v[28:31], v[208:211], v[0:3]
	v_mfma_f32_16x16x32_bf16 v[4:7], v[116:119], v[208:211], v[4:7]
	v_mfma_f32_16x16x32_bf16 v[146:149], v[28:31], v[182:185], v[146:149]
	v_mfma_f32_16x16x32_bf16 v[150:153], v[116:119], v[182:185], v[150:153]
	v_mfma_f32_16x16x32_bf16 v[154:157], v[28:31], v[190:193], v[154:157]
	v_mfma_f32_16x16x32_bf16 v[158:161], v[116:119], v[190:193], v[158:161]
	v_mfma_f32_16x16x32_bf16 v[162:165], v[28:31], v[198:201], v[162:165]
	v_mfma_f32_16x16x32_bf16 v[166:169], v[116:119], v[198:201], v[166:169]
	v_mfma_f32_16x16x32_bf16 v[8:11], v[120:123], v[178:181], v[8:11]
	v_mfma_f32_16x16x32_bf16 v[12:15], v[170:173], v[178:181], v[12:15]
	v_mfma_f32_16x16x32_bf16 v[24:27], v[120:123], v[186:189], v[60:63]
	v_mfma_f32_16x16x32_bf16 v[28:31], v[170:173], v[186:189], v[100:103]
	v_mfma_f32_16x16x32_bf16 v[60:63], v[120:123], v[194:197], v[104:107]
	v_mfma_f32_16x16x32_bf16 v[100:103], v[170:173], v[194:197], v[108:111]
	v_mfma_f32_16x16x32_bf16 v[16:19], v[120:123], v[204:207], v[16:19]
	v_mfma_f32_16x16x32_bf16 v[20:23], v[170:173], v[204:207], v[20:23]
	v_mfma_f32_16x16x32_bf16 v[8:11], v[124:127], v[182:185], v[8:11]
	v_mfma_f32_16x16x32_bf16 v[12:15], v[174:177], v[182:185], v[12:15]
	v_mfma_f32_16x16x32_bf16 v[24:27], v[124:127], v[190:193], v[24:27]
	v_mfma_f32_16x16x32_bf16 v[28:31], v[174:177], v[190:193], v[28:31]
	v_mfma_f32_16x16x32_bf16 v[60:63], v[124:127], v[198:201], v[60:63]
	v_mfma_f32_16x16x32_bf16 v[100:103], v[174:177], v[198:201], v[100:103]
	v_mfma_f32_16x16x32_bf16 v[16:19], v[124:127], v[208:211], v[16:19]
	v_mfma_f32_16x16x32_bf16 v[20:23], v[174:177], v[208:211], v[20:23]
	s_barrier
	ds_read_b128 v[104:107], v140
	ds_read_b128 v[108:111], v140 offset:1024
	ds_read_b128 v[112:115], v140 offset:2048
	ds_read_b128 v[116:119], v140 offset:3072
	ds_read_b128 v[120:123], v141
	ds_read_b128 v[124:127], v141 offset:1024
	ds_read_b128 v[170:173], v141 offset:2048
	ds_read_b128 v[174:177], v141 offset:3072
	s_add_u32 s42, s42, 0x10180
	s_addc_u32 s43, s43, 0
	s_mov_b32 m0, s59
	v_lshl_add_u64 v[212:213], s[42:43], 0, v[128:129]
	ds_read_b128 v[178:181], v142
	ds_read_b128 v[182:185], v142 offset:1024
	ds_read_b128 v[186:189], v142 offset:2048
	ds_read_b128 v[190:193], v142 offset:3072
	ds_read_b128 v[194:197], v142 offset:4096
	ds_read_b128 v[198:201], v142 offset:5120
	ds_read_b128 v[204:207], v142 offset:6144
	ds_read_b128 v[208:211], v142 offset:7168
	global_load_lds_dwordx4 v[212:213], off
	s_mov_b32 m0, s60
	v_lshl_add_u64 v[212:213], s[42:43], 0, v[132:133]
	global_load_lds_dwordx4 v[212:213], off
	s_waitcnt vmcnt(8)
	s_waitcnt lgkmcnt(0)
	s_barrier
	s_waitcnt lgkmcnt(0)
	v_mfma_f32_16x16x32_bf16 v[64:67], v[104:107], v[178:181], v[64:67]
	v_mfma_f32_16x16x32_bf16 v[68:71], v[112:115], v[178:181], v[68:71]
	v_mfma_f32_16x16x32_bf16 v[72:75], v[104:107], v[186:189], v[72:75]
	v_mfma_f32_16x16x32_bf16 v[76:79], v[112:115], v[186:189], v[76:79]
	v_mfma_f32_16x16x32_bf16 v[80:83], v[104:107], v[194:197], v[80:83]
	v_mfma_f32_16x16x32_bf16 v[84:87], v[112:115], v[194:197], v[84:87]
	v_mfma_f32_16x16x32_bf16 v[88:91], v[104:107], v[204:207], v[88:91]
	v_mfma_f32_16x16x32_bf16 v[92:95], v[112:115], v[204:207], v[92:95]
	v_mfma_f32_16x16x32_bf16 v[64:67], v[108:111], v[182:185], v[64:67]
	v_mfma_f32_16x16x32_bf16 v[68:71], v[116:119], v[182:185], v[68:71]
	v_mfma_f32_16x16x32_bf16 v[72:75], v[108:111], v[190:193], v[72:75]
	v_mfma_f32_16x16x32_bf16 v[76:79], v[116:119], v[190:193], v[76:79]
	v_mfma_f32_16x16x32_bf16 v[80:83], v[108:111], v[198:201], v[80:83]
	v_mfma_f32_16x16x32_bf16 v[84:87], v[116:119], v[198:201], v[84:87]
	v_mfma_f32_16x16x32_bf16 v[88:91], v[108:111], v[208:211], v[88:91]
	v_mfma_f32_16x16x32_bf16 v[92:95], v[116:119], v[208:211], v[92:95]
	v_mfma_f32_16x16x32_bf16 v[32:35], v[170:173], v[178:181], v[32:35]
	v_mfma_f32_16x16x32_bf16 v[36:39], v[120:123], v[186:189], v[36:39]
	v_mfma_f32_16x16x32_bf16 v[40:43], v[170:173], v[186:189], v[40:43]
	v_mfma_f32_16x16x32_bf16 v[44:47], v[120:123], v[194:197], v[44:47]
	v_mfma_f32_16x16x32_bf16 v[48:51], v[170:173], v[194:197], v[48:51]
	v_mfma_f32_16x16x32_bf16 v[52:55], v[120:123], v[204:207], v[52:55]
	v_mfma_f32_16x16x32_bf16 v[56:59], v[170:173], v[204:207], v[56:59]
	v_mfma_f32_16x16x32_bf16 v[96:99], v[120:123], v[178:181], v[96:99]
	v_mfma_f32_16x16x32_bf16 v[32:35], v[174:177], v[182:185], v[32:35]
	v_mfma_f32_16x16x32_bf16 v[36:39], v[124:127], v[190:193], v[36:39]
	v_mfma_f32_16x16x32_bf16 v[40:43], v[174:177], v[190:193], v[40:43]
	v_mfma_f32_16x16x32_bf16 v[44:47], v[124:127], v[198:201], v[44:47]
	v_mfma_f32_16x16x32_bf16 v[48:51], v[174:177], v[198:201], v[48:51]
	v_mfma_f32_16x16x32_bf16 v[52:55], v[124:127], v[208:211], v[52:55]
	v_mfma_f32_16x16x32_bf16 v[56:59], v[174:177], v[208:211], v[56:59]
	v_mfma_f32_16x16x32_bf16 v[212:215], v[124:127], v[182:185], v[96:99]
	s_barrier
; #define PG8_STAGE(bufoff, gbase, voff) do { _Pragma("unroll") for (int _i = 0; _i < 2; ++_i) \
;         __builtin_amdgcn_global_load_lds((const unsigned*)((const char*)(gbase) + (voff)[_i]), (LAS unsigned*)(lds + (bufoff) + ldsw + _i * 8192), 16, 0, 0); } while (0)
; #define PG8_LDA(dst, b, h) do { _Pragma("unroll") for (int m = 0; m < 4; ++m) _Pragma("unroll") for (int k = 0; k < 2; ++k) dst[m][k] = *(const LAS bf16x8*)(lds + PG8_SA(b, h) + aoff + m * 2048 + k * 1024); } while (0)
; #define PG8_LDB(dst, b, h) do { _Pragma("unroll") for (int n = 0; n < 2; ++n) _Pragma("unroll") for (int k = 0; k < 2; ++k) dst[n][k] = *(const LAS bf16x8*)(lds + PG8_SB(b, h) + boff + n * 2048 + k * 1024); } while (0)
; #define PG8_MMA(ai, bj, At, Bt) do { __builtin_amdgcn_s_setprio(1); _Pragma("unroll") for (int m = 0; m < 4; ++m) _Pragma("unroll") for (int n = 0; n < 2; ++n) _Pragma("unroll") for (int k = 0; k < 2; ++k) \
;         acc[ai][bj][m][n] = __builtin_amdgcn_mfma_f32_16x16x32_bf16(Bt[n][k], At[m][k], acc[ai][bj][m][n], 0, 0, 0); __builtin_amdgcn_s_setprio(0); } while (0)
; #define PG8_WAIT_V(n) asm volatile("s_waitcnt vmcnt(" #n ")" ::: "memory")
; #define PG8_WAIT_L(n) asm volatile("s_waitcnt lgkmcnt(" #n ")" ::: "memory")
; #define PG8_BAR __builtin_amdgcn_s_barrier()
; #define PG8_SCHED __builtin_amdgcn_sched_barrier(0)
; template <class Epi, class Sched, bool ALIGN_EPI = true>
; __device__ __forceinline__ void gemm_phase(LAS unsigned char* lds, const Gemm g, const Sched& S, const Epi& E) {
;     ...
;             PG8_LDA(At, 0, 1); PG8_STAGE(PG8_SB(0, 0), b2, voffB); PG8_STAGE(PG8_SB(0, 1), b2 + hstep, voffB); PG8_STAGE(PG8_SA(0, 0), a2, voffA);
;             PG8_WAIT_V(8); PG8_WAIT_L(0); PG8_BAR; PG8_MMA(1, 0, At, B0); PG8_MMA(1, 1, At, B1); PG8_BAR; PG8_SCHED;
;             PG8_LDB(B0, 1, 0); PG8_LDB(B1, 1, 1); PG8_SCHED; PG8_LDA(At, 1, 0); PG8_STAGE(PG8_SA(0, 1), a2 + hstep, voffA);
;             PG8_WAIT_V(8); PG8_WAIT_L(0); PG8_BAR; PG8_MMA(0, 0, At, B0); PG8_MMA(0, 1, At, B1); PG8_BAR; PG8_SCHED;
	s_mov_b32 m0, s61
	v_lshl_add_u64 v[248:249], s[40:41], 0, v[130:131]
	s_add_u32 s42, s40, 0x10000
	ds_read_b128 v[96:99], v142 offset:16384
	ds_read_b128 v[178:181], v142 offset:17408
	ds_read_b128 v[182:185], v142 offset:18432
	ds_read_b128 v[186:189], v142 offset:19456
	ds_read_b128 v[190:193], v142 offset:20480
	ds_read_b128 v[194:197], v142 offset:21504
	ds_read_b128 v[198:201], v142 offset:22528
	ds_read_b128 v[204:207], v142 offset:23552
	global_load_lds_dwordx4 v[248:249], off
	v_lshl_add_u64 v[250:251], s[40:41], 0, v[134:135]
	s_mov_b32 m0, s62
	s_addc_u32 s43, s41, 0
	global_load_lds_dwordx4 v[250:251], off
	v_lshl_add_u64 v[208:209], s[42:43], 0, v[130:131]
	s_mov_b32 m0, s63
	v_lshl_add_u64 v[252:253], s[44:45], 0, v[128:129]
	global_load_lds_dwordx4 v[208:209], off
	v_lshl_add_u64 v[208:209], s[42:43], 0, v[134:135]
	s_mov_b32 m0, s76
	v_lshl_add_u64 v[202:203], s[44:45], 0, v[132:133]
	global_load_lds_dwordx4 v[208:209], off
	s_mov_b32 m0, s23
	s_nop 0
	global_load_lds_dwordx4 v[252:253], off
	s_mov_b32 m0, s53
	s_nop 0
	global_load_lds_dwordx4 v[202:203], off
	s_waitcnt vmcnt(8)
	s_waitcnt lgkmcnt(0)
	s_barrier
	s_waitcnt lgkmcnt(0)
	v_mfma_f32_16x16x32_bf16 v[0:3], v[104:107], v[198:201], v[0:3]
	v_mfma_f32_16x16x32_bf16 v[4:7], v[112:115], v[198:201], v[4:7]
	v_mfma_f32_16x16x32_bf16 v[146:149], v[104:107], v[96:99], v[146:149]
	v_mfma_f32_16x16x32_bf16 v[150:153], v[112:115], v[96:99], v[150:153]
	v_mfma_f32_16x16x32_bf16 v[154:157], v[104:107], v[182:185], v[154:157]
	v_mfma_f32_16x16x32_bf16 v[158:161], v[112:115], v[182:185], v[158:161]
	v_mfma_f32_16x16x32_bf16 v[162:165], v[104:107], v[190:193], v[162:165]
	v_mfma_f32_16x16x32_bf16 v[166:169], v[112:115], v[190:193], v[166:169]
	v_mfma_f32_16x16x32_bf16 v[0:3], v[108:111], v[204:207], v[0:3]
	v_mfma_f32_16x16x32_bf16 v[4:7], v[116:119], v[204:207], v[4:7]
	v_mfma_f32_16x16x32_bf16 v[146:149], v[108:111], v[178:181], v[146:149]
	v_mfma_f32_16x16x32_bf16 v[150:153], v[116:119], v[178:181], v[150:153]
	v_mfma_f32_16x16x32_bf16 v[154:157], v[108:111], v[186:189], v[154:157]
	v_mfma_f32_16x16x32_bf16 v[158:161], v[116:119], v[186:189], v[158:161]
	v_mfma_f32_16x16x32_bf16 v[162:165], v[108:111], v[194:197], v[162:165]
	v_mfma_f32_16x16x32_bf16 v[166:169], v[116:119], v[194:197], v[166:169]
	v_mfma_f32_16x16x32_bf16 v[8:11], v[120:123], v[96:99], v[8:11]
	v_mfma_f32_16x16x32_bf16 v[12:15], v[170:173], v[96:99], v[12:15]
	v_mfma_f32_16x16x32_bf16 v[24:27], v[120:123], v[182:185], v[24:27]
	v_mfma_f32_16x16x32_bf16 v[8:11], v[124:127], v[178:181], v[8:11]
	v_mfma_f32_16x16x32_bf16 v[12:15], v[174:177], v[178:181], v[12:15]
	v_mfma_f32_16x16x32_bf16 v[178:181], v[124:127], v[186:189], v[24:27]
	v_mfma_f32_16x16x32_bf16 v[24:27], v[170:173], v[182:185], v[28:31]
	v_mfma_f32_16x16x32_bf16 v[182:185], v[174:177], v[186:189], v[24:27]
	v_mfma_f32_16x16x32_bf16 v[24:27], v[120:123], v[190:193], v[60:63]
	v_mfma_f32_16x16x32_bf16 v[186:189], v[124:127], v[194:197], v[24:27]
	v_mfma_f32_16x16x32_bf16 v[24:27], v[170:173], v[190:193], v[100:103]
	v_mfma_f32_16x16x32_bf16 v[16:19], v[120:123], v[198:201], v[16:19]
	v_mfma_f32_16x16x32_bf16 v[190:193], v[174:177], v[194:197], v[24:27]
	v_mfma_f32_16x16x32_bf16 v[194:197], v[124:127], v[204:207], v[16:19]
	v_mfma_f32_16x16x32_bf16 v[16:19], v[170:173], v[198:201], v[20:23]
	v_mfma_f32_16x16x32_bf16 v[170:173], v[174:177], v[204:207], v[16:19]
	s_barrier
	ds_read_b128 v[60:63], v143
	ds_read_b128 v[174:177], v143 offset:1024
	ds_read_b128 v[198:201], v143 offset:2048
	ds_read_b128 v[204:207], v143 offset:3072
	ds_read_b128 v[208:211], v144
	ds_read_b128 v[216:219], v144 offset:1024
	ds_read_b128 v[220:223], v144 offset:2048
	ds_read_b128 v[224:227], v144 offset:3072
	s_add_u32 s42, s44, 0x10000
	s_addc_u32 s43, s45, 0
	s_mov_b32 m0, s54
	v_lshl_add_u64 v[24:25], s[42:43], 0, v[128:129]
	ds_read_b128 v[16:19], v142 offset:32768
	ds_read_b128 v[20:23], v142 offset:33792
	ds_read_b128 v[108:111], v142 offset:34816
	ds_read_b128 v[228:231], v142 offset:35840
	ds_read_b128 v[232:235], v142 offset:36864
	ds_read_b128 v[236:239], v142 offset:37888
	ds_read_b128 v[240:243], v142 offset:38912
	ds_read_b128 v[244:247], v142 offset:39936
	global_load_lds_dwordx4 v[24:25], off
	s_mov_b32 m0, s55
	v_lshl_add_u64 v[24:25], s[42:43], 0, v[132:133]
	global_load_lds_dwordx4 v[24:25], off
	s_waitcnt vmcnt(8)
	s_waitcnt lgkmcnt(0)
	s_barrier
; #define PG8_STAGE(bufoff, gbase, voff) do { _Pragma("unroll") for (int _i = 0; _i < 2; ++_i) \
;         __builtin_amdgcn_global_load_lds((const unsigned*)((const char*)(gbase) + (voff)[_i]), (LAS unsigned*)(lds + (bufoff) + ldsw + _i * 8192), 16, 0, 0); } while (0)
; #define PG8_LDA(dst, b, h) do { _Pragma("unroll") for (int m = 0; m < 4; ++m) _Pragma("unroll") for (int k = 0; k < 2; ++k) dst[m][k] = *(const LAS bf16x8*)(lds + PG8_SA(b, h) + aoff + m * 2048 + k * 1024); } while (0)
; #define PG8_MMA(ai, bj, At, Bt) do { __builtin_amdgcn_s_setprio(1); _Pragma("unroll") for (int m = 0; m < 4; ++m) _Pragma("unroll") for (int n = 0; n < 2; ++n) _Pragma("unroll") for (int k = 0; k < 2; ++k) \
;         acc[ai][bj][m][n] = __builtin_amdgcn_mfma_f32_16x16x32_bf16(Bt[n][k], At[m][k], acc[ai][bj][m][n], 0, 0, 0); __builtin_amdgcn_s_setprio(0); } while (0)
; #define PG8_WAIT_V(n) asm volatile("s_waitcnt vmcnt(" #n ")" ::: "memory")
; #define PG8_WAIT_L(n) asm volatile("s_waitcnt lgkmcnt(" #n ")" ::: "memory")
; #define PG8_BAR __builtin_amdgcn_s_barrier()
; #define PG8_SCHED __builtin_amdgcn_sched_barrier(0)
; template <class Epi, class Sched, bool ALIGN_EPI = true>
; __device__ __forceinline__ void gemm_phase(LAS unsigned char* lds, const Gemm g, const Sched& S, const Epi& E) {
;     ...
;             PG8_WAIT_V(8); PG8_WAIT_L(0); PG8_BAR; PG8_MMA(0, 0, At, B0); PG8_MMA(0, 1, At, B1); PG8_BAR; PG8_SCHED;
;             PG8_LDA(At, 1, 1); PG8_STAGE(PG8_SB(1, 0), b3, voffB); PG8_STAGE(PG8_SB(1, 1), b3 + hstep, voffB); PG8_STAGE(PG8_SA(1, 0), a3, voffA);
;             PG8_WAIT_V(8); PG8_WAIT_L(0); PG8_BAR; PG8_MMA(1, 0, At, B0); PG8_MMA(1, 1, At, B1); PG8_BAR; PG8_SCHED;
;         }
;         if constexpr (ALIGN_EPI) { if (wr == 0) PG8_BAR; }
	s_waitcnt lgkmcnt(0)
	v_mfma_f32_16x16x32_bf16 v[24:27], v[60:63], v[16:19], v[64:67]
	v_mfma_f32_16x16x32_bf16 v[112:115], v[174:177], v[20:23], v[24:27]
	v_mfma_f32_16x16x32_bf16 v[24:27], v[198:201], v[16:19], v[68:71]
	v_mfma_f32_16x16x32_bf16 v[116:119], v[204:207], v[20:23], v[24:27]
	v_mfma_f32_16x16x32_bf16 v[24:27], v[60:63], v[108:111], v[72:75]
	v_mfma_f32_16x16x32_bf16 v[96:99], v[174:177], v[228:231], v[24:27]
	v_mfma_f32_16x16x32_bf16 v[24:27], v[198:201], v[108:111], v[76:79]
	v_mfma_f32_16x16x32_bf16 v[100:103], v[204:207], v[228:231], v[24:27]
	v_mfma_f32_16x16x32_bf16 v[24:27], v[60:63], v[232:235], v[80:83]
	v_mfma_f32_16x16x32_bf16 v[64:67], v[174:177], v[236:239], v[24:27]
	v_mfma_f32_16x16x32_bf16 v[24:27], v[198:201], v[232:235], v[84:87]
	v_mfma_f32_16x16x32_bf16 v[68:71], v[204:207], v[236:239], v[24:27]
	v_mfma_f32_16x16x32_bf16 v[24:27], v[60:63], v[240:243], v[88:91]
	v_mfma_f32_16x16x32_bf16 v[28:31], v[198:201], v[240:243], v[92:95]
	v_mfma_f32_16x16x32_bf16 v[24:27], v[174:177], v[244:247], v[24:27]
	v_mfma_f32_16x16x32_bf16 v[28:31], v[204:207], v[244:247], v[28:31]
	v_mfma_f32_16x16x32_bf16 v[72:75], v[208:211], v[16:19], v[212:215]
	v_mfma_f32_16x16x32_bf16 v[16:19], v[220:223], v[16:19], v[32:35]
	v_mfma_f32_16x16x32_bf16 v[124:127], v[224:227], v[20:23], v[16:19]
	v_mfma_f32_16x16x32_bf16 v[16:19], v[208:211], v[108:111], v[36:39]
	v_mfma_f32_16x16x32_bf16 v[104:107], v[216:219], v[228:231], v[16:19]
	v_mfma_f32_16x16x32_bf16 v[16:19], v[220:223], v[108:111], v[40:43]
	v_mfma_f32_16x16x32_bf16 v[108:111], v[224:227], v[228:231], v[16:19]
	v_mfma_f32_16x16x32_bf16 v[16:19], v[208:211], v[232:235], v[44:47]
	v_mfma_f32_16x16x32_bf16 v[120:123], v[216:219], v[20:23], v[72:75]
	v_mfma_f32_16x16x32_bf16 v[72:75], v[216:219], v[236:239], v[16:19]
	v_mfma_f32_16x16x32_bf16 v[16:19], v[220:223], v[232:235], v[48:51]
	v_mfma_f32_16x16x32_bf16 v[76:79], v[224:227], v[236:239], v[16:19]
	v_mfma_f32_16x16x32_bf16 v[16:19], v[208:211], v[240:243], v[52:55]
	v_mfma_f32_16x16x32_bf16 v[40:43], v[216:219], v[244:247], v[16:19]
	v_mfma_f32_16x16x32_bf16 v[16:19], v[220:223], v[240:243], v[56:59]
	v_mfma_f32_16x16x32_bf16 v[44:47], v[224:227], v[244:247], v[16:19]
	s_barrier
	s_mov_b32 m0, s77
	s_nop 3
	v_lshl_add_u64 v[16:17], v[248:249], 0, s[12:13]
	s_add_u32 s40, s40, 0x10080
	ds_read_b128 v[32:35], v142 offset:49152
	ds_read_b128 v[36:39], v142 offset:50176
	ds_read_b128 v[212:215], v142 offset:51200
	ds_read_b128 v[228:231], v142 offset:52224
	ds_read_b128 v[232:235], v142 offset:53248
	ds_read_b128 v[236:239], v142 offset:54272
	ds_read_b128 v[240:243], v142 offset:55296
	ds_read_b128 v[244:247], v142 offset:56320
	global_load_lds_dwordx4 v[16:17], off
	v_lshl_add_u64 v[16:17], v[250:251], 0, s[12:13]
	s_mov_b32 m0, s78
	s_addc_u32 s41, s41, 0
	global_load_lds_dwordx4 v[16:17], off
	s_mov_b32 m0, s79
	s_nop 0
	global_load_lds_dwordx4 v130, s[40:41]
	s_mov_b32 m0, s80
	s_nop 0
	global_load_lds_dwordx4 v134, s[40:41]
	s_mov_b32 m0, s57
	v_lshl_add_u64 v[16:17], v[252:253], 0, s[12:13]
	global_load_lds_dwordx4 v[16:17], off
	s_mov_b32 m0, s58
	v_lshl_add_u64 v[16:17], v[202:203], 0, s[12:13]
	global_load_lds_dwordx4 v[16:17], off
	s_waitcnt vmcnt(8)
	s_waitcnt lgkmcnt(0)
	s_barrier
	s_waitcnt lgkmcnt(0)
	v_mfma_f32_16x16x32_bf16 v[16:19], v[60:63], v[32:35], v[146:149]
	v_mfma_f32_16x16x32_bf16 v[80:83], v[174:177], v[36:39], v[16:19]
	v_mfma_f32_16x16x32_bf16 v[16:19], v[198:201], v[32:35], v[150:153]
	v_mfma_f32_16x16x32_bf16 v[84:87], v[204:207], v[36:39], v[16:19]
	v_mfma_f32_16x16x32_bf16 v[16:19], v[60:63], v[212:215], v[154:157]
	v_mfma_f32_16x16x32_bf16 v[48:51], v[174:177], v[228:231], v[16:19]
	v_mfma_f32_16x16x32_bf16 v[16:19], v[198:201], v[212:215], v[158:161]
	v_mfma_f32_16x16x32_bf16 v[52:55], v[204:207], v[228:231], v[16:19]
	v_mfma_f32_16x16x32_bf16 v[16:19], v[60:63], v[232:235], v[162:165]
	v_mfma_f32_16x16x32_bf16 v[20:23], v[198:201], v[232:235], v[166:169]
	v_mfma_f32_16x16x32_bf16 v[0:3], v[60:63], v[240:243], v[0:3]
	v_mfma_f32_16x16x32_bf16 v[4:7], v[198:201], v[240:243], v[4:7]
	v_mfma_f32_16x16x32_bf16 v[16:19], v[174:177], v[236:239], v[16:19]
	v_mfma_f32_16x16x32_bf16 v[20:23], v[204:207], v[236:239], v[20:23]
	v_mfma_f32_16x16x32_bf16 v[0:3], v[174:177], v[244:247], v[0:3]
	v_mfma_f32_16x16x32_bf16 v[4:7], v[204:207], v[244:247], v[4:7]
	v_mfma_f32_16x16x32_bf16 v[8:11], v[208:211], v[32:35], v[8:11]
	v_mfma_f32_16x16x32_bf16 v[88:91], v[216:219], v[36:39], v[8:11]
	v_mfma_f32_16x16x32_bf16 v[8:11], v[220:223], v[32:35], v[12:15]
	v_mfma_f32_16x16x32_bf16 v[92:95], v[224:227], v[36:39], v[8:11]
	v_mfma_f32_16x16x32_bf16 v[8:11], v[208:211], v[212:215], v[178:181]
	v_mfma_f32_16x16x32_bf16 v[56:59], v[216:219], v[228:231], v[8:11]
	v_mfma_f32_16x16x32_bf16 v[8:11], v[220:223], v[212:215], v[182:185]
	v_mfma_f32_16x16x32_bf16 v[60:63], v[224:227], v[228:231], v[8:11]
	v_mfma_f32_16x16x32_bf16 v[8:11], v[208:211], v[232:235], v[186:189]
	v_mfma_f32_16x16x32_bf16 v[32:35], v[216:219], v[236:239], v[8:11]
	v_mfma_f32_16x16x32_bf16 v[8:11], v[220:223], v[232:235], v[190:193]
	v_mfma_f32_16x16x32_bf16 v[36:39], v[224:227], v[236:239], v[8:11]
	v_mfma_f32_16x16x32_bf16 v[8:11], v[208:211], v[240:243], v[194:197]
	v_mfma_f32_16x16x32_bf16 v[12:15], v[220:223], v[240:243], v[170:173]
	v_mfma_f32_16x16x32_bf16 v[8:11], v[216:219], v[244:247], v[8:11]
	v_mfma_f32_16x16x32_bf16 v[12:15], v[224:227], v[244:247], v[12:15]
	s_barrier
	s_and_b64 vcc, exec, s[4:5]
	s_cbranch_vccnz .LBB0_669
	s_barrier
